# K-loops: the 16 redundant s_waitcnt lgkmcnt(0) behind the segment barriers removed; on top of v97
# speedup vs baseline: 1.0039x; 1.0019x over previous
; #define PG8_STAGE(bufoff, gbase, voff) do { _Pragma("unroll") for (int _i = 0; _i < 2; ++_i) \
;         __builtin_amdgcn_global_load_lds((const unsigned*)((const char*)(gbase) + (voff)[_i]), (PG8_LAS unsigned*)(lds + (bufoff) + ldsw + _i * 8192), 16, 0, 0); } while (0)
; #define PG8_LDA(dst, b, h) do { _Pragma("unroll") for (int m = 0; m < 4; ++m) _Pragma("unroll") for (int k = 0; k < 2; ++k) dst[m][k] = *(const PG8_LAS bf16x8*)(lds + PG8_SA(b, h) + aoff + m * 2048 + k * 1024); } while (0)
; #define PG8_WAIT_V(n) asm volatile("s_waitcnt vmcnt(" #n ")" ::: "memory")
; #define PG8_WAIT_L(n) asm volatile("s_waitcnt lgkmcnt(" #n ")" ::: "memory")
; #define PG8_BAR __builtin_amdgcn_s_barrier()
; #define PG8_SCHED __builtin_amdgcn_sched_barrier(0)
;     ...
;             PG8_WAIT_V(8); PG8_WAIT_L(0); PG8_BAR; PG8_MMA(0, 0, At, B0); PG8_MMA(0, 1, At, B1); PG8_BAR; PG8_SCHED;
;             PG8_LDA(At, 0, 1); PG8_STAGE(PG8_SB(0, 0), b2, voffB); PG8_STAGE(PG8_SB(0, 1), b2 + hstepB, voffB); PG8_STAGE(PG8_SA(0, 0), a2, voffA);
;             PG8_WAIT_V(8); PG8_WAIT_L(0); PG8_BAR; PG8_MMA(1, 0, At, B0); PG8_MMA(1, 1, At, B1); PG8_BAR; PG8_SCHED;
.Lpka_da:
	s_waitcnt lgkmcnt(0)
	s_barrier
	v_mfma_f32_16x16x32_bf16 v[132:135], v[144:147], v[210:213], v[132:135]
	v_mfma_f32_16x16x32_bf16 v[128:131], v[152:155], v[210:213], v[128:131]
	v_mfma_f32_16x16x32_bf16 v[116:119], v[144:147], v[218:221], v[116:119]
	v_mfma_f32_16x16x32_bf16 v[112:115], v[152:155], v[218:221], v[112:115]
	v_mfma_f32_16x16x32_bf16 v[100:103], v[144:147], v[226:229], v[100:103]
	v_mfma_f32_16x16x32_bf16 v[96:99], v[152:155], v[226:229], v[96:99]
	v_mfma_f32_16x16x32_bf16 v[84:87], v[144:147], v[234:237], v[84:87]
	v_mfma_f32_16x16x32_bf16 v[80:83], v[152:155], v[234:237], v[80:83]
	v_mfma_f32_16x16x32_bf16 v[132:135], v[148:151], v[214:217], v[132:135]
	v_mfma_f32_16x16x32_bf16 v[128:131], v[156:159], v[214:217], v[128:131]
	v_mfma_f32_16x16x32_bf16 v[116:119], v[148:151], v[222:225], v[116:119]
	v_mfma_f32_16x16x32_bf16 v[112:115], v[156:159], v[222:225], v[112:115]
	v_mfma_f32_16x16x32_bf16 v[100:103], v[148:151], v[230:233], v[100:103]
	v_mfma_f32_16x16x32_bf16 v[96:99], v[156:159], v[230:233], v[96:99]
	v_mfma_f32_16x16x32_bf16 v[84:87], v[148:151], v[238:241], v[84:87]
	v_mfma_f32_16x16x32_bf16 v[80:83], v[156:159], v[238:241], v[80:83]
	v_mfma_f32_16x16x32_bf16 v[140:143], v[186:189], v[210:213], v[140:143]
	v_mfma_f32_16x16x32_bf16 v[136:139], v[202:205], v[210:213], v[136:139]
	v_mfma_f32_16x16x32_bf16 v[124:127], v[186:189], v[218:221], v[124:127]
	v_mfma_f32_16x16x32_bf16 v[120:123], v[202:205], v[218:221], v[120:123]
	v_mfma_f32_16x16x32_bf16 v[108:111], v[186:189], v[226:229], v[108:111]
	v_mfma_f32_16x16x32_bf16 v[104:107], v[202:205], v[226:229], v[104:107]
	v_mfma_f32_16x16x32_bf16 v[92:95], v[186:189], v[234:237], v[92:95]
	v_mfma_f32_16x16x32_bf16 v[88:91], v[202:205], v[234:237], v[88:91]
	v_mfma_f32_16x16x32_bf16 v[140:143], v[198:201], v[214:217], v[140:143]
	v_mfma_f32_16x16x32_bf16 v[136:139], v[206:209], v[214:217], v[136:139]
	v_mfma_f32_16x16x32_bf16 v[124:127], v[198:201], v[222:225], v[124:127]
	v_mfma_f32_16x16x32_bf16 v[120:123], v[206:209], v[222:225], v[120:123]
	v_mfma_f32_16x16x32_bf16 v[108:111], v[198:201], v[230:233], v[108:111]
	v_mfma_f32_16x16x32_bf16 v[104:107], v[206:209], v[230:233], v[104:107]
	v_mfma_f32_16x16x32_bf16 v[92:95], v[198:201], v[238:241], v[92:95]
	v_mfma_f32_16x16x32_bf16 v[88:91], v[206:209], v[238:241], v[88:91]
	s_barrier
	s_add_i32 s82, s82, s15
	s_mov_b32 m0, s82
	ds_read_b128 v[210:213], v197 offset:16384
	ds_read_b128 v[214:217], v197 offset:17408
	ds_read_b128 v[218:221], v197 offset:18432
	ds_read_b128 v[222:225], v197 offset:19456
	ds_read_b128 v[226:229], v197 offset:20480
	ds_read_b128 v[230:233], v197 offset:21504
	ds_read_b128 v[234:237], v197 offset:22528
	ds_read_b128 v[238:241], v197 offset:23552
	global_load_lds_dwordx4 v170, s[72:73]
	s_add_i32 m0, s82, 0x2000
	s_add_u32 s82, s72, 0x10000
	s_addc_u32 s83, s73, 0
	s_add_i32 s86, s86, s15
	global_load_lds_dwordx4 v166, s[72:73]
	s_mov_b32 m0, s86
	s_nop 0
	global_load_lds_dwordx4 v170, s[82:83]
	s_add_i32 m0, s86, 0x2000
	s_nop 0
	global_load_lds_dwordx4 v166, s[82:83]
	s_mov_b32 m0, s63
	s_nop 0
	global_load_lds_dwordx4 v172, s[76:77]
	s_mov_b32 m0, s64
	s_nop 0
	global_load_lds_dwordx4 v168, s[76:77]
	s_lshl_b32 s100, s100, 1
	s_and_b32 s100, s100, 6
	s_bcnt1_i32_b32 vcc_lo, s100
	s_cmp_eq_u32 vcc_lo, 0
	s_cbranch_scc1 .Lpka_w8b
	s_cmp_eq_u32 vcc_lo, 1
	s_cbranch_scc1 .Lpka_w9b
	s_waitcnt vmcnt(10)
	s_branch .Lpka_db

; #define PG8_STAGE(bufoff, gbase, voff) do { _Pragma("unroll") for (int _i = 0; _i < 2; ++_i) \
;         __builtin_amdgcn_global_load_lds((const unsigned*)((const char*)(gbase) + (voff)[_i]), (PG8_LAS unsigned*)(lds + (bufoff) + ldsw + _i * 8192), 16, 0, 0); } while (0)
; #define PG8_LDA(dst, b, h) do { _Pragma("unroll") for (int m = 0; m < 4; ++m) _Pragma("unroll") for (int k = 0; k < 2; ++k) dst[m][k] = *(const PG8_LAS bf16x8*)(lds + PG8_SA(b, h) + aoff + m * 2048 + k * 1024); } while (0)
; #define PG8_LDB(dst, b, h) do { _Pragma("unroll") for (int n = 0; n < 2; ++n) _Pragma("unroll") for (int k = 0; k < 2; ++k) dst[n][k] = *(const PG8_LAS bf16x8*)(lds + PG8_SB(b, h) + boff + n * 2048 + k * 1024); } while (0)
; #define PG8_WAIT_V(n) asm volatile("s_waitcnt vmcnt(" #n ")" ::: "memory")
; #define PG8_WAIT_L(n) asm volatile("s_waitcnt lgkmcnt(" #n ")" ::: "memory")
; #define PG8_BAR __builtin_amdgcn_s_barrier()
; #define PG8_SCHED __builtin_amdgcn_sched_barrier(0)
;     ...
;             PG8_WAIT_V(8); PG8_WAIT_L(0); PG8_BAR; PG8_MMA(1, 0, At, B0); PG8_MMA(1, 1, At, B1); PG8_BAR; PG8_SCHED;
;             PG8_LDB(B0, 1, 0); PG8_LDB(B1, 1, 1); PG8_SCHED; PG8_LDA(At, 1, 0); PG8_STAGE(PG8_SA(0, 1), a2 + hstep, voffA);
;             PG8_WAIT_V(8); PG8_WAIT_L(0); PG8_BAR; PG8_MMA(0, 0, At, B0); PG8_MMA(0, 1, At, B1); PG8_BAR; PG8_SCHED;
.Lpka_db:
	s_waitcnt lgkmcnt(0)
	s_barrier
	v_mfma_f32_16x16x32_bf16 v[68:71], v[144:147], v[210:213], v[68:71]
	v_mfma_f32_16x16x32_bf16 v[64:67], v[152:155], v[210:213], v[64:67]
	v_mfma_f32_16x16x32_bf16 v[52:55], v[144:147], v[218:221], v[52:55]
	v_mfma_f32_16x16x32_bf16 v[48:51], v[152:155], v[218:221], v[48:51]
	v_mfma_f32_16x16x32_bf16 v[36:39], v[144:147], v[226:229], v[36:39]
	v_mfma_f32_16x16x32_bf16 v[32:35], v[152:155], v[226:229], v[32:35]
	v_mfma_f32_16x16x32_bf16 v[20:23], v[144:147], v[234:237], v[20:23]
	v_mfma_f32_16x16x32_bf16 v[16:19], v[152:155], v[234:237], v[16:19]
	v_mfma_f32_16x16x32_bf16 v[68:71], v[148:151], v[214:217], v[68:71]
	v_mfma_f32_16x16x32_bf16 v[64:67], v[156:159], v[214:217], v[64:67]
	v_mfma_f32_16x16x32_bf16 v[52:55], v[148:151], v[222:225], v[52:55]
	v_mfma_f32_16x16x32_bf16 v[48:51], v[156:159], v[222:225], v[48:51]
	v_mfma_f32_16x16x32_bf16 v[36:39], v[148:151], v[230:233], v[36:39]
	v_mfma_f32_16x16x32_bf16 v[32:35], v[156:159], v[230:233], v[32:35]
	v_mfma_f32_16x16x32_bf16 v[20:23], v[148:151], v[238:241], v[20:23]
	v_mfma_f32_16x16x32_bf16 v[16:19], v[156:159], v[238:241], v[16:19]
	v_mfma_f32_16x16x32_bf16 v[76:79], v[186:189], v[210:213], v[76:79]
	v_mfma_f32_16x16x32_bf16 v[72:75], v[202:205], v[210:213], v[72:75]
	v_mfma_f32_16x16x32_bf16 v[60:63], v[186:189], v[218:221], v[60:63]
	v_mfma_f32_16x16x32_bf16 v[56:59], v[202:205], v[218:221], v[56:59]
	v_mfma_f32_16x16x32_bf16 v[44:47], v[186:189], v[226:229], v[44:47]
	v_mfma_f32_16x16x32_bf16 v[40:43], v[202:205], v[226:229], v[40:43]
	v_mfma_f32_16x16x32_bf16 v[24:27], v[186:189], v[234:237], v[24:27]
	v_mfma_f32_16x16x32_bf16 v[28:31], v[202:205], v[234:237], v[28:31]
	v_mfma_f32_16x16x32_bf16 v[76:79], v[198:201], v[214:217], v[76:79]
	v_mfma_f32_16x16x32_bf16 v[72:75], v[206:209], v[214:217], v[72:75]
	v_mfma_f32_16x16x32_bf16 v[60:63], v[198:201], v[222:225], v[60:63]
	v_mfma_f32_16x16x32_bf16 v[56:59], v[206:209], v[222:225], v[56:59]
	v_mfma_f32_16x16x32_bf16 v[44:47], v[198:201], v[230:233], v[44:47]
	v_mfma_f32_16x16x32_bf16 v[40:43], v[206:209], v[230:233], v[40:43]
	v_mfma_f32_16x16x32_bf16 v[24:27], v[198:201], v[238:241], v[24:27]
	v_mfma_f32_16x16x32_bf16 v[28:31], v[206:209], v[238:241], v[28:31]
	s_barrier
	s_add_i32 s82, 0, 0x18000
	s_add_i32 s83, 0, 0x1c000
	v_add_u32_e32 v156, s82, v195
	v_add_u32_e32 v183, s83, v195
	ds_read_b128 v[144:147], v156
	ds_read_b128 v[148:151], v156 offset:1024
	ds_read_b128 v[152:155], v156 offset:2048
	ds_read_b128 v[156:159], v156 offset:3072
	ds_read_b128 v[186:189], v183
	ds_read_b128 v[198:201], v183 offset:1024
	ds_read_b128 v[202:205], v183 offset:2048
	ds_read_b128 v[206:209], v183 offset:3072
	s_add_u32 s76, s76, 0x40000
	s_addc_u32 s77, s77, 0
	s_mov_b32 m0, s65
	ds_read_b128 v[210:213], v197 offset:32768
	ds_read_b128 v[214:217], v197 offset:33792
	ds_read_b128 v[218:221], v197 offset:34816
	ds_read_b128 v[222:225], v197 offset:35840
	ds_read_b128 v[226:229], v197 offset:36864
	ds_read_b128 v[230:233], v197 offset:37888
	ds_read_b128 v[234:237], v197 offset:38912
	ds_read_b128 v[238:241], v197 offset:39936
	global_load_lds_dwordx4 v172, s[76:77]
	s_mov_b32 m0, s66
	s_nop 0
	global_load_lds_dwordx4 v168, s[76:77]
	s_lshl_b32 s100, s100, 1
	s_and_b32 s100, s100, 6
	s_cmp_eq_u32 s101, 0
	s_cbranch_scc1 .Lpka_nc
	s_cmp_lt_i32 s81, 2
	s_cbranch_scc1 .Lpka_nc
	s_or_b32 s100, s100, 1
	s_cmp_eq_u32 s101, 8
	s_cbranch_scc1 .Lpka_s0c
	s_cmp_eq_u32 s101, 7
	s_cbranch_scc1 .Lpka_s1c
	s_cmp_eq_u32 s101, 6
	s_cbranch_scc1 .Lpka_s2c
	s_cmp_eq_u32 s101, 5
	s_cbranch_scc1 .Lpka_s3c
	s_cmp_eq_u32 s101, 4
	s_cbranch_scc1 .Lpka_s4c
	s_cmp_eq_u32 s101, 3
	s_cbranch_scc1 .Lpka_s5c
	s_cmp_eq_u32 s101, 2
	s_cbranch_scc1 .Lpka_s6c
	global_store_dwordx4 v[254:255], v[12:15], off offset:64
	s_branch .Lpka_ic

; #define PG8_STAGE(bufoff, gbase, voff) do { _Pragma("unroll") for (int _i = 0; _i < 2; ++_i) \
;         __builtin_amdgcn_global_load_lds((const unsigned*)((const char*)(gbase) + (voff)[_i]), (PG8_LAS unsigned*)(lds + (bufoff) + ldsw + _i * 8192), 16, 0, 0); } while (0)
; #define PG8_LDA(dst, b, h) do { _Pragma("unroll") for (int m = 0; m < 4; ++m) _Pragma("unroll") for (int k = 0; k < 2; ++k) dst[m][k] = *(const PG8_LAS bf16x8*)(lds + PG8_SA(b, h) + aoff + m * 2048 + k * 1024); } while (0)
; #define PG8_WAIT_V(n) asm volatile("s_waitcnt vmcnt(" #n ")" ::: "memory")
; #define PG8_WAIT_L(n) asm volatile("s_waitcnt lgkmcnt(" #n ")" ::: "memory")
; #define PG8_BAR __builtin_amdgcn_s_barrier()
; #define PG8_SCHED __builtin_amdgcn_sched_barrier(0)
;     ...
;             PG8_WAIT_V(8); PG8_WAIT_L(0); PG8_BAR; PG8_MMA(0, 0, At, B0); PG8_MMA(0, 1, At, B1); PG8_BAR; PG8_SCHED;
;             PG8_LDA(At, 1, 1); PG8_STAGE(PG8_SB(1, 0), b3, voffB); PG8_STAGE(PG8_SB(1, 1), b3 + hstepB, voffB); PG8_STAGE(PG8_SA(1, 0), a3, voffA);
;             PG8_WAIT_V(8); PG8_WAIT_L(0); PG8_BAR; PG8_MMA(1, 0, At, B0); PG8_MMA(1, 1, At, B1); PG8_BAR; PG8_SCHED;
.Lpka_dc:
	s_waitcnt lgkmcnt(0)
	s_barrier
	v_mfma_f32_16x16x32_bf16 v[132:135], v[144:147], v[210:213], v[132:135]
	v_mfma_f32_16x16x32_bf16 v[128:131], v[152:155], v[210:213], v[128:131]
	v_mfma_f32_16x16x32_bf16 v[116:119], v[144:147], v[218:221], v[116:119]
	v_mfma_f32_16x16x32_bf16 v[112:115], v[152:155], v[218:221], v[112:115]
	v_mfma_f32_16x16x32_bf16 v[100:103], v[144:147], v[226:229], v[100:103]
	v_mfma_f32_16x16x32_bf16 v[96:99], v[152:155], v[226:229], v[96:99]
	v_mfma_f32_16x16x32_bf16 v[84:87], v[144:147], v[234:237], v[84:87]
	v_mfma_f32_16x16x32_bf16 v[80:83], v[152:155], v[234:237], v[80:83]
	v_mfma_f32_16x16x32_bf16 v[132:135], v[148:151], v[214:217], v[132:135]
	v_mfma_f32_16x16x32_bf16 v[128:131], v[156:159], v[214:217], v[128:131]
	v_mfma_f32_16x16x32_bf16 v[116:119], v[148:151], v[222:225], v[116:119]
	v_mfma_f32_16x16x32_bf16 v[112:115], v[156:159], v[222:225], v[112:115]
	v_mfma_f32_16x16x32_bf16 v[100:103], v[148:151], v[230:233], v[100:103]
	v_mfma_f32_16x16x32_bf16 v[96:99], v[156:159], v[230:233], v[96:99]
	v_mfma_f32_16x16x32_bf16 v[84:87], v[148:151], v[238:241], v[84:87]
	v_mfma_f32_16x16x32_bf16 v[80:83], v[156:159], v[238:241], v[80:83]
	v_mfma_f32_16x16x32_bf16 v[140:143], v[186:189], v[210:213], v[140:143]
	v_mfma_f32_16x16x32_bf16 v[136:139], v[202:205], v[210:213], v[136:139]
	v_mfma_f32_16x16x32_bf16 v[124:127], v[186:189], v[218:221], v[124:127]
	v_mfma_f32_16x16x32_bf16 v[120:123], v[202:205], v[218:221], v[120:123]
	v_mfma_f32_16x16x32_bf16 v[108:111], v[186:189], v[226:229], v[108:111]
	v_mfma_f32_16x16x32_bf16 v[104:107], v[202:205], v[226:229], v[104:107]
	v_mfma_f32_16x16x32_bf16 v[92:95], v[186:189], v[234:237], v[92:95]
	v_mfma_f32_16x16x32_bf16 v[88:91], v[202:205], v[234:237], v[88:91]
	v_mfma_f32_16x16x32_bf16 v[140:143], v[198:201], v[214:217], v[140:143]
	v_mfma_f32_16x16x32_bf16 v[136:139], v[206:209], v[214:217], v[136:139]
	v_mfma_f32_16x16x32_bf16 v[124:127], v[198:201], v[222:225], v[124:127]
	v_mfma_f32_16x16x32_bf16 v[120:123], v[206:209], v[222:225], v[120:123]
	v_mfma_f32_16x16x32_bf16 v[108:111], v[198:201], v[230:233], v[108:111]
	v_mfma_f32_16x16x32_bf16 v[104:107], v[206:209], v[230:233], v[104:107]
	v_mfma_f32_16x16x32_bf16 v[92:95], v[198:201], v[238:241], v[92:95]
	v_mfma_f32_16x16x32_bf16 v[88:91], v[206:209], v[238:241], v[88:91]
	s_barrier
	s_add_i32 m0, s82, s15
	s_add_u32 vcc_lo, s72, 0x80
	s_addc_u32 vcc_hi, s73, 0
	ds_read_b128 v[210:213], v197 offset:49152
	ds_read_b128 v[214:217], v197 offset:50176
	ds_read_b128 v[218:221], v197 offset:51200
	ds_read_b128 v[222:225], v197 offset:52224
	ds_read_b128 v[226:229], v197 offset:53248
	ds_read_b128 v[230:233], v197 offset:54272
	ds_read_b128 v[234:237], v197 offset:55296
	ds_read_b128 v[238:241], v197 offset:56320
	global_load_lds_dwordx4 v170, vcc
	s_add_i32 m0, m0, 0x2000
	s_nop 0
	global_load_lds_dwordx4 v166, vcc
	s_add_u32 s72, s72, 0x10080
	s_addc_u32 s73, s73, 0
	s_add_i32 m0, s83, s15
	s_nop 0
	global_load_lds_dwordx4 v170, s[72:73]
	s_add_i32 m0, m0, 0x2000
	s_nop 0
	global_load_lds_dwordx4 v166, s[72:73]
	s_add_u32 vcc_lo, s76, 0xfffc0080
	s_addc_u32 vcc_hi, s77, -1
	s_mov_b32 m0, s74
	s_nop 0
	global_load_lds_dwordx4 v172, vcc
	s_mov_b32 m0, s75
	s_nop 0
	global_load_lds_dwordx4 v168, vcc
	s_lshl_b32 s100, s100, 1
	s_and_b32 s100, s100, 6
	s_bcnt1_i32_b32 vcc_lo, s100
	s_cmp_eq_u32 vcc_lo, 0
	s_cbranch_scc1 .Lpka_w8e
	s_cmp_eq_u32 vcc_lo, 1
	s_cbranch_scc1 .Lpka_w9e
	s_waitcnt vmcnt(10)
	s_branch .Lpka_de

; #define PG8_WAIT_V(n) asm volatile("s_waitcnt vmcnt(" #n ")" ::: "memory")
; #define PG8_WAIT_L(n) asm volatile("s_waitcnt lgkmcnt(" #n ")" ::: "memory")
; #define PG8_BAR __builtin_amdgcn_s_barrier()
; #define PG8_SCHED __builtin_amdgcn_sched_barrier(0)
;     ...
;             PG8_WAIT_V(8); PG8_WAIT_L(0); PG8_BAR; PG8_MMA(1, 0, At, B0); PG8_MMA(1, 1, At, B1); PG8_BAR; PG8_SCHED;
;         }
;         if constexpr (ALIGN_EPI) { if (wr == 0) PG8_BAR; }
.Lpka_de:
	s_waitcnt lgkmcnt(0)
	s_barrier
	v_mfma_f32_16x16x32_bf16 v[68:71], v[144:147], v[210:213], v[68:71]
	v_mfma_f32_16x16x32_bf16 v[64:67], v[152:155], v[210:213], v[64:67]
	v_mfma_f32_16x16x32_bf16 v[52:55], v[144:147], v[218:221], v[52:55]
	v_mfma_f32_16x16x32_bf16 v[48:51], v[152:155], v[218:221], v[48:51]
	v_mfma_f32_16x16x32_bf16 v[36:39], v[144:147], v[226:229], v[36:39]
	v_mfma_f32_16x16x32_bf16 v[32:35], v[152:155], v[226:229], v[32:35]
	v_mfma_f32_16x16x32_bf16 v[20:23], v[144:147], v[234:237], v[20:23]
	v_mfma_f32_16x16x32_bf16 v[16:19], v[152:155], v[234:237], v[16:19]
	v_mfma_f32_16x16x32_bf16 v[68:71], v[148:151], v[214:217], v[68:71]
	v_mfma_f32_16x16x32_bf16 v[64:67], v[156:159], v[214:217], v[64:67]
	v_mfma_f32_16x16x32_bf16 v[52:55], v[148:151], v[222:225], v[52:55]
	v_mfma_f32_16x16x32_bf16 v[48:51], v[156:159], v[222:225], v[48:51]
	v_mfma_f32_16x16x32_bf16 v[36:39], v[148:151], v[230:233], v[36:39]
	v_mfma_f32_16x16x32_bf16 v[32:35], v[156:159], v[230:233], v[32:35]
	v_mfma_f32_16x16x32_bf16 v[20:23], v[148:151], v[238:241], v[20:23]
	v_mfma_f32_16x16x32_bf16 v[16:19], v[156:159], v[238:241], v[16:19]
	v_mfma_f32_16x16x32_bf16 v[76:79], v[186:189], v[210:213], v[76:79]
	v_mfma_f32_16x16x32_bf16 v[72:75], v[202:205], v[210:213], v[72:75]
	v_mfma_f32_16x16x32_bf16 v[60:63], v[186:189], v[218:221], v[60:63]
	v_mfma_f32_16x16x32_bf16 v[56:59], v[202:205], v[218:221], v[56:59]
	v_mfma_f32_16x16x32_bf16 v[44:47], v[186:189], v[226:229], v[44:47]
	v_mfma_f32_16x16x32_bf16 v[40:43], v[202:205], v[226:229], v[40:43]
	v_mfma_f32_16x16x32_bf16 v[24:27], v[186:189], v[234:237], v[24:27]
	v_mfma_f32_16x16x32_bf16 v[28:31], v[202:205], v[234:237], v[28:31]
	v_mfma_f32_16x16x32_bf16 v[76:79], v[198:201], v[214:217], v[76:79]
	v_mfma_f32_16x16x32_bf16 v[72:75], v[206:209], v[214:217], v[72:75]
	v_mfma_f32_16x16x32_bf16 v[60:63], v[198:201], v[222:225], v[60:63]
	v_mfma_f32_16x16x32_bf16 v[56:59], v[206:209], v[222:225], v[56:59]
	v_mfma_f32_16x16x32_bf16 v[44:47], v[198:201], v[230:233], v[44:47]
	v_mfma_f32_16x16x32_bf16 v[40:43], v[206:209], v[230:233], v[40:43]
	v_mfma_f32_16x16x32_bf16 v[24:27], v[198:201], v[238:241], v[24:27]
	v_mfma_f32_16x16x32_bf16 v[28:31], v[206:209], v[238:241], v[28:31]
	s_barrier
	s_add_i32 s81, s81, 2
	s_add_u32 s38, s38, 0x100
	s_addc_u32 s39, s39, 0
	s_add_u32 s61, s61, 0x100
	s_addc_u32 s80, s80, 0
	s_cmp_gt_u32 s81, 13
	s_cbranch_scc0 .LBB0_206
	v_mov_b32_e32 v162, 0x500
	v_mov_b32_e32 v163, 0
	v_mov_b32_e32 v164, 0x4ff
	v_mov_b32_e32 v165, 0
	v_mov_b32_e32 v190, 0x358637bd
	v_mov_b32_e32 v191, 1
	v_mov_b32_e32 v192, 0x300
	v_mov_b32_e32 v193, 0x200
	s_and_b64 vcc, exec, s[22:23]
	s_cbranch_vccz .LBB0_209
	s_barrier

; #define PG8_STAGE(bufoff, gbase, voff) do { _Pragma("unroll") for (int _i = 0; _i < 2; ++_i) \
;         __builtin_amdgcn_global_load_lds((const unsigned*)((const char*)(gbase) + (voff)[_i]), (PG8_LAS unsigned*)(lds + (bufoff) + ldsw + _i * 8192), 16, 0, 0); } while (0)
; #define PG8_LDA(dst, b, h) do { _Pragma("unroll") for (int m = 0; m < 4; ++m) _Pragma("unroll") for (int k = 0; k < 2; ++k) dst[m][k] = *(const PG8_LAS bf16x8*)(lds + PG8_SA(b, h) + aoff + m * 2048 + k * 1024); } while (0)
; #define PG8_LDB(dst, b, h) do { _Pragma("unroll") for (int n = 0; n < 2; ++n) _Pragma("unroll") for (int k = 0; k < 2; ++k) dst[n][k] = *(const PG8_LAS bf16x8*)(lds + PG8_SB(b, h) + boff + n * 2048 + k * 1024); } while (0)
; #define PG8_WAIT_V(n) asm volatile("s_waitcnt vmcnt(" #n ")" ::: "memory")
; #define PG8_WAIT_L(n) asm volatile("s_waitcnt lgkmcnt(" #n ")" ::: "memory")
; #define PG8_BAR __builtin_amdgcn_s_barrier()
; #define PG8_SCHED __builtin_amdgcn_sched_barrier(0)
;     ...
;         const bool has_next = S.next(ui + 1, nxt);
;         const char* nA = has_next ? (const char*)g.A + (size_t)nxt.pm * tstep : cA; const char* nB = has_next ? (const char*)g.Bt + (size_t)nxt.pn * tstep : cB;
;         for (int t = 0; t < nt; t += 2) {
;             const bool last = (t == nt - 2);
;             const char* a1 = cA + (size_t)(t + 1) * kstep;
;             const char* a2 = last ? nA : cA + (size_t)(t + 2) * kstep; const char* b2 = last ? nB : cB + (size_t)(t + 2) * kstep;
;             const char* a3 = a2 + kstep; const char* b3 = b2 + kstep;
;             PG8_LDB(B0, 0, 0); PG8_LDB(B1, 0, 1); PG8_SCHED; PG8_LDA(At, 0, 0); PG8_STAGE(PG8_SA(1, 1), a1 + hstep, voffA);
;             PG8_WAIT_V(8); PG8_WAIT_L(0); PG8_BAR; PG8_MMA(0, 0, At, B0); PG8_MMA(0, 1, At, B1); PG8_BAR; PG8_SCHED;
;             PG8_LDA(At, 0, 1); PG8_STAGE(PG8_SB(0, 0), b2, voffB); PG8_STAGE(PG8_SB(0, 1), b2 + hstepB, voffB); PG8_STAGE(PG8_SA(0, 0), a2, voffA);
;             PG8_WAIT_V(8); PG8_WAIT_L(0); PG8_BAR; PG8_MMA(1, 0, At, B0); PG8_MMA(1, 1, At, B1); PG8_BAR; PG8_SCHED;
;             PG8_LDB(B0, 1, 0); PG8_LDB(B1, 1, 1); PG8_SCHED; PG8_LDA(At, 1, 0); PG8_STAGE(PG8_SA(0, 1), a2 + hstep, voffA);
.LBB0_434:
	v_add_u32_e32 v140, s49, v199
	s_waitcnt lgkmcnt(0)
	v_add_u32_e32 v156, s50, v199
	ds_read_b128 v[128:131], v140
	ds_read_b128 v[132:135], v140 offset:1024
	ds_read_b128 v[136:139], v140 offset:2048
	ds_read_b128 v[140:143], v140 offset:3072
	ds_read_b128 v[144:147], v156
	ds_read_b128 v[148:151], v156 offset:1024
	ds_read_b128 v[152:155], v156 offset:2048
	ds_read_b128 v[156:159], v156 offset:3072
	s_add_u32 s22, s24, 0xfffc0080
	s_addc_u32 s23, s25, -1
	s_cmp_eq_u32 s54, 12
	s_cselect_b32 s27, s2, s23
	s_cselect_b32 s26, s15, s22
	s_cselect_b32 s23, s13, s53
	s_cselect_b32 s22, s21, s52
	v_lshl_add_u64 v[196:197], s[24:25], 0, v[184:185]
	s_add_i32 m0, s29, 0xc000
	ds_read_b128 v[160:163], v201
	ds_read_b128 v[164:167], v201 offset:1024
	ds_read_b128 v[168:171], v201 offset:2048
	ds_read_b128 v[172:175], v201 offset:3072
	ds_read_b128 v[192:195], v201 offset:4096
	ds_read_b128 v[202:205], v201 offset:5120
	ds_read_b128 v[206:209], v201 offset:6144
	ds_read_b128 v[210:213], v201 offset:7168
	global_load_lds_dwordx4 v[196:197], off
	v_lshl_add_u64 v[196:197], s[24:25], 0, v[186:187]
	s_add_i32 m0, s29, 0xe000
	s_nop 0
	global_load_lds_dwordx4 v[196:197], off
	s_waitcnt vmcnt(8)
	s_waitcnt lgkmcnt(0)
	s_barrier
	v_mfma_f32_16x16x32_bf16 v[112:115], v[128:131], v[160:163], v[112:115]
	v_mfma_f32_16x16x32_bf16 v[116:119], v[136:139], v[160:163], v[116:119]
	v_mfma_f32_16x16x32_bf16 v[108:111], v[128:131], v[168:171], v[108:111]
	v_mfma_f32_16x16x32_bf16 v[104:107], v[136:139], v[168:171], v[104:107]
	v_mfma_f32_16x16x32_bf16 v[92:95], v[128:131], v[192:195], v[92:95]
	v_mfma_f32_16x16x32_bf16 v[88:91], v[136:139], v[192:195], v[88:91]
	v_mfma_f32_16x16x32_bf16 v[76:79], v[128:131], v[206:209], v[76:79]
	v_mfma_f32_16x16x32_bf16 v[72:75], v[136:139], v[206:209], v[72:75]
	v_mfma_f32_16x16x32_bf16 v[112:115], v[132:135], v[164:167], v[112:115]
	v_mfma_f32_16x16x32_bf16 v[116:119], v[140:143], v[164:167], v[116:119]
	v_mfma_f32_16x16x32_bf16 v[108:111], v[132:135], v[172:175], v[108:111]
	v_mfma_f32_16x16x32_bf16 v[104:107], v[140:143], v[172:175], v[104:107]
	v_mfma_f32_16x16x32_bf16 v[92:95], v[132:135], v[202:205], v[92:95]
	v_mfma_f32_16x16x32_bf16 v[88:91], v[140:143], v[202:205], v[88:91]
	v_mfma_f32_16x16x32_bf16 v[76:79], v[132:135], v[210:213], v[76:79]
	v_mfma_f32_16x16x32_bf16 v[72:75], v[140:143], v[210:213], v[72:75]
	v_mfma_f32_16x16x32_bf16 v[120:123], v[144:147], v[160:163], v[120:123]
	v_mfma_f32_16x16x32_bf16 v[124:127], v[152:155], v[160:163], v[124:127]
	v_mfma_f32_16x16x32_bf16 v[100:103], v[144:147], v[168:171], v[100:103]
	v_mfma_f32_16x16x32_bf16 v[96:99], v[152:155], v[168:171], v[96:99]
	v_mfma_f32_16x16x32_bf16 v[84:87], v[144:147], v[192:195], v[84:87]
	v_mfma_f32_16x16x32_bf16 v[80:83], v[152:155], v[192:195], v[80:83]
	v_mfma_f32_16x16x32_bf16 v[68:71], v[144:147], v[206:209], v[68:71]
	v_mfma_f32_16x16x32_bf16 v[64:67], v[152:155], v[206:209], v[64:67]
	v_mfma_f32_16x16x32_bf16 v[120:123], v[148:151], v[164:167], v[120:123]
	v_mfma_f32_16x16x32_bf16 v[124:127], v[156:159], v[164:167], v[124:127]
	v_mfma_f32_16x16x32_bf16 v[100:103], v[148:151], v[172:175], v[100:103]
	v_mfma_f32_16x16x32_bf16 v[96:99], v[156:159], v[172:175], v[96:99]
	v_mfma_f32_16x16x32_bf16 v[84:87], v[148:151], v[202:205], v[84:87]
	v_mfma_f32_16x16x32_bf16 v[80:83], v[156:159], v[202:205], v[80:83]
	v_mfma_f32_16x16x32_bf16 v[68:71], v[148:151], v[210:213], v[68:71]
	v_mfma_f32_16x16x32_bf16 v[64:67], v[156:159], v[210:213], v[64:67]
	s_barrier
	s_add_i32 s55, s49, s28
	v_lshl_add_u64 v[196:197], s[22:23], 0, v[178:179]
	s_mov_b32 m0, s55
	ds_read_b128 v[160:163], v201 offset:16384
	ds_read_b128 v[164:167], v201 offset:17408
	ds_read_b128 v[168:171], v201 offset:18432
	ds_read_b128 v[172:175], v201 offset:19456
	ds_read_b128 v[192:195], v201 offset:20480
	ds_read_b128 v[202:205], v201 offset:21504
	ds_read_b128 v[206:209], v201 offset:22528
	ds_read_b128 v[210:213], v201 offset:23552
	global_load_lds_dwordx4 v[196:197], off
	s_add_i32 m0, s55, 0x2000
	s_add_u32 s56, s22, 0x40000
	v_lshl_add_u64 v[214:215], s[22:23], 0, v[176:177]
	s_addc_u32 s57, s23, 0
	s_add_i32 s55, s50, s28
	global_load_lds_dwordx4 v[214:215], off
	v_lshl_add_u64 v[216:217], s[56:57], 0, v[178:179]
	s_mov_b32 m0, s55
	v_lshl_add_u64 v[218:219], s[26:27], 0, v[176:177]
	global_load_lds_dwordx4 v[216:217], off
	v_lshl_add_u64 v[216:217], s[56:57], 0, v[176:177]
	s_add_i32 m0, s55, 0x2000
	s_nop 0
	global_load_lds_dwordx4 v[216:217], off
	v_lshl_add_u64 v[216:217], s[26:27], 0, v[178:179]
	s_mov_b32 m0, s29
	s_nop 0
	global_load_lds_dwordx4 v[216:217], off
	s_mov_b32 m0, s33
	s_nop 0
	global_load_lds_dwordx4 v[218:219], off
	s_waitcnt vmcnt(8)
	s_waitcnt lgkmcnt(0)
	s_barrier
; #define PG8_STAGE(bufoff, gbase, voff) do { _Pragma("unroll") for (int _i = 0; _i < 2; ++_i) \
;         __builtin_amdgcn_global_load_lds((const unsigned*)((const char*)(gbase) + (voff)[_i]), (PG8_LAS unsigned*)(lds + (bufoff) + ldsw + _i * 8192), 16, 0, 0); } while (0)
; #define PG8_LDA(dst, b, h) do { _Pragma("unroll") for (int m = 0; m < 4; ++m) _Pragma("unroll") for (int k = 0; k < 2; ++k) dst[m][k] = *(const PG8_LAS bf16x8*)(lds + PG8_SA(b, h) + aoff + m * 2048 + k * 1024); } while (0)
; #define PG8_WAIT_V(n) asm volatile("s_waitcnt vmcnt(" #n ")" ::: "memory")
; #define PG8_WAIT_L(n) asm volatile("s_waitcnt lgkmcnt(" #n ")" ::: "memory")
; #define PG8_BAR __builtin_amdgcn_s_barrier()
; #define PG8_SCHED __builtin_amdgcn_sched_barrier(0)
;     ...
;             PG8_WAIT_V(8); PG8_WAIT_L(0); PG8_BAR; PG8_MMA(0, 0, At, B0); PG8_MMA(0, 1, At, B1); PG8_BAR; PG8_SCHED;
;             PG8_LDA(At, 1, 1); PG8_STAGE(PG8_SB(1, 0), b3, voffB); PG8_STAGE(PG8_SB(1, 1), b3 + hstepB, voffB); PG8_STAGE(PG8_SA(1, 0), a3, voffA);
;             PG8_WAIT_V(8); PG8_WAIT_L(0); PG8_BAR; PG8_MMA(1, 0, At, B0); PG8_MMA(1, 1, At, B1); PG8_BAR; PG8_SCHED;
	v_mfma_f32_16x16x32_bf16 v[60:63], v[128:131], v[160:163], v[60:63]
	v_mfma_f32_16x16x32_bf16 v[52:55], v[136:139], v[160:163], v[52:55]
	v_mfma_f32_16x16x32_bf16 v[44:47], v[128:131], v[168:171], v[44:47]
	v_mfma_f32_16x16x32_bf16 v[36:39], v[136:139], v[168:171], v[36:39]
	v_mfma_f32_16x16x32_bf16 v[28:31], v[128:131], v[192:195], v[28:31]
	v_mfma_f32_16x16x32_bf16 v[20:23], v[136:139], v[192:195], v[20:23]
	v_mfma_f32_16x16x32_bf16 v[8:11], v[128:131], v[206:209], v[8:11]
	v_mfma_f32_16x16x32_bf16 v[0:3], v[136:139], v[206:209], v[0:3]
	v_mfma_f32_16x16x32_bf16 v[60:63], v[132:135], v[164:167], v[60:63]
	v_mfma_f32_16x16x32_bf16 v[52:55], v[140:143], v[164:167], v[52:55]
	v_mfma_f32_16x16x32_bf16 v[44:47], v[132:135], v[172:175], v[44:47]
	v_mfma_f32_16x16x32_bf16 v[36:39], v[140:143], v[172:175], v[36:39]
	v_mfma_f32_16x16x32_bf16 v[28:31], v[132:135], v[202:205], v[28:31]
	v_mfma_f32_16x16x32_bf16 v[20:23], v[140:143], v[202:205], v[20:23]
	v_mfma_f32_16x16x32_bf16 v[8:11], v[132:135], v[210:213], v[8:11]
	v_mfma_f32_16x16x32_bf16 v[0:3], v[140:143], v[210:213], v[0:3]
	v_mfma_f32_16x16x32_bf16 v[56:59], v[144:147], v[160:163], v[56:59]
	v_mfma_f32_16x16x32_bf16 v[48:51], v[152:155], v[160:163], v[48:51]
	v_mfma_f32_16x16x32_bf16 v[40:43], v[144:147], v[168:171], v[40:43]
	v_mfma_f32_16x16x32_bf16 v[32:35], v[152:155], v[168:171], v[32:35]
	v_mfma_f32_16x16x32_bf16 v[24:27], v[144:147], v[192:195], v[24:27]
	v_mfma_f32_16x16x32_bf16 v[16:19], v[152:155], v[192:195], v[16:19]
	v_mfma_f32_16x16x32_bf16 v[4:7], v[144:147], v[206:209], v[4:7]
	v_mfma_f32_16x16x32_bf16 v[12:15], v[152:155], v[206:209], v[12:15]
	v_mfma_f32_16x16x32_bf16 v[56:59], v[148:151], v[164:167], v[56:59]
	v_mfma_f32_16x16x32_bf16 v[48:51], v[156:159], v[164:167], v[48:51]
	v_mfma_f32_16x16x32_bf16 v[40:43], v[148:151], v[172:175], v[40:43]
	v_mfma_f32_16x16x32_bf16 v[32:35], v[156:159], v[172:175], v[32:35]
	v_mfma_f32_16x16x32_bf16 v[24:27], v[148:151], v[202:205], v[24:27]
	v_mfma_f32_16x16x32_bf16 v[16:19], v[156:159], v[202:205], v[16:19]
	v_mfma_f32_16x16x32_bf16 v[4:7], v[148:151], v[210:213], v[4:7]
	v_mfma_f32_16x16x32_bf16 v[12:15], v[156:159], v[210:213], v[12:15]
	s_barrier
	s_add_i32 s55, 0, 0x18000
	s_add_i32 s56, 0, 0x1c000
	v_add_u32_e32 v140, s55, v199
	v_add_u32_e32 v156, s56, v199
	ds_read_b128 v[128:131], v140
	ds_read_b128 v[132:135], v140 offset:1024
	ds_read_b128 v[136:139], v140 offset:2048
	ds_read_b128 v[140:143], v140 offset:3072
	ds_read_b128 v[144:147], v156
	ds_read_b128 v[148:151], v156 offset:1024
	ds_read_b128 v[152:155], v156 offset:2048
	ds_read_b128 v[156:159], v156 offset:3072
	s_add_u32 s26, s26, 0x40000
	s_addc_u32 s27, s27, 0
	s_mov_b32 m0, s36
	v_lshl_add_u64 v[220:221], s[26:27], 0, v[178:179]
	ds_read_b128 v[160:163], v201 offset:32768
	ds_read_b128 v[164:167], v201 offset:33792
	ds_read_b128 v[168:171], v201 offset:34816
	ds_read_b128 v[172:175], v201 offset:35840
	ds_read_b128 v[192:195], v201 offset:36864
	ds_read_b128 v[202:205], v201 offset:37888
	ds_read_b128 v[206:209], v201 offset:38912
	ds_read_b128 v[210:213], v201 offset:39936
	global_load_lds_dwordx4 v[220:221], off
	v_lshl_add_u64 v[220:221], s[26:27], 0, v[176:177]
	s_mov_b32 m0, s37
	s_nop 0
	global_load_lds_dwordx4 v[220:221], off
	s_waitcnt vmcnt(8)
	s_waitcnt lgkmcnt(0)
	s_barrier
	v_mfma_f32_16x16x32_bf16 v[112:115], v[128:131], v[160:163], v[112:115]
	v_mfma_f32_16x16x32_bf16 v[116:119], v[136:139], v[160:163], v[116:119]
	v_mfma_f32_16x16x32_bf16 v[108:111], v[128:131], v[168:171], v[108:111]
	v_mfma_f32_16x16x32_bf16 v[104:107], v[136:139], v[168:171], v[104:107]
	v_mfma_f32_16x16x32_bf16 v[92:95], v[128:131], v[192:195], v[92:95]
	v_mfma_f32_16x16x32_bf16 v[88:91], v[136:139], v[192:195], v[88:91]
	v_mfma_f32_16x16x32_bf16 v[76:79], v[128:131], v[206:209], v[76:79]
	v_mfma_f32_16x16x32_bf16 v[72:75], v[136:139], v[206:209], v[72:75]
	v_mfma_f32_16x16x32_bf16 v[112:115], v[132:135], v[164:167], v[112:115]
	v_mfma_f32_16x16x32_bf16 v[116:119], v[140:143], v[164:167], v[116:119]
	v_mfma_f32_16x16x32_bf16 v[108:111], v[132:135], v[172:175], v[108:111]
	v_mfma_f32_16x16x32_bf16 v[104:107], v[140:143], v[172:175], v[104:107]
	v_mfma_f32_16x16x32_bf16 v[92:95], v[132:135], v[202:205], v[92:95]
	v_mfma_f32_16x16x32_bf16 v[88:91], v[140:143], v[202:205], v[88:91]
	v_mfma_f32_16x16x32_bf16 v[76:79], v[132:135], v[210:213], v[76:79]
	v_mfma_f32_16x16x32_bf16 v[72:75], v[140:143], v[210:213], v[72:75]
	v_mfma_f32_16x16x32_bf16 v[120:123], v[144:147], v[160:163], v[120:123]
	v_mfma_f32_16x16x32_bf16 v[124:127], v[152:155], v[160:163], v[124:127]
	v_mfma_f32_16x16x32_bf16 v[100:103], v[144:147], v[168:171], v[100:103]
	v_mfma_f32_16x16x32_bf16 v[96:99], v[152:155], v[168:171], v[96:99]
	v_mfma_f32_16x16x32_bf16 v[84:87], v[144:147], v[192:195], v[84:87]
	v_mfma_f32_16x16x32_bf16 v[80:83], v[152:155], v[192:195], v[80:83]
	v_mfma_f32_16x16x32_bf16 v[68:71], v[144:147], v[206:209], v[68:71]
	v_mfma_f32_16x16x32_bf16 v[64:67], v[152:155], v[206:209], v[64:67]
	v_mfma_f32_16x16x32_bf16 v[120:123], v[148:151], v[164:167], v[120:123]
	v_mfma_f32_16x16x32_bf16 v[124:127], v[156:159], v[164:167], v[124:127]
	v_mfma_f32_16x16x32_bf16 v[100:103], v[148:151], v[172:175], v[100:103]
	v_mfma_f32_16x16x32_bf16 v[96:99], v[156:159], v[172:175], v[96:99]
	v_mfma_f32_16x16x32_bf16 v[84:87], v[148:151], v[202:205], v[84:87]
	v_mfma_f32_16x16x32_bf16 v[80:83], v[156:159], v[202:205], v[80:83]
	v_mfma_f32_16x16x32_bf16 v[68:71], v[148:151], v[210:213], v[68:71]
	v_mfma_f32_16x16x32_bf16 v[64:67], v[156:159], v[210:213], v[64:67]
	s_barrier
; #define PG8_STAGE(bufoff, gbase, voff) do { _Pragma("unroll") for (int _i = 0; _i < 2; ++_i) \
;         __builtin_amdgcn_global_load_lds((const unsigned*)((const char*)(gbase) + (voff)[_i]), (PG8_LAS unsigned*)(lds + (bufoff) + ldsw + _i * 8192), 16, 0, 0); } while (0)
; #define PG8_LDA(dst, b, h) do { _Pragma("unroll") for (int m = 0; m < 4; ++m) _Pragma("unroll") for (int k = 0; k < 2; ++k) dst[m][k] = *(const PG8_LAS bf16x8*)(lds + PG8_SA(b, h) + aoff + m * 2048 + k * 1024); } while (0)
; #define PG8_WAIT_V(n) asm volatile("s_waitcnt vmcnt(" #n ")" ::: "memory")
; #define PG8_WAIT_L(n) asm volatile("s_waitcnt lgkmcnt(" #n ")" ::: "memory")
; #define PG8_BAR __builtin_amdgcn_s_barrier()
; #define PG8_SCHED __builtin_amdgcn_sched_barrier(0)
;     ...
;             PG8_LDA(At, 1, 1); PG8_STAGE(PG8_SB(1, 0), b3, voffB); PG8_STAGE(PG8_SB(1, 1), b3 + hstepB, voffB); PG8_STAGE(PG8_SA(1, 0), a3, voffA);
;             PG8_WAIT_V(8); PG8_WAIT_L(0); PG8_BAR; PG8_MMA(1, 0, At, B0); PG8_MMA(1, 1, At, B1); PG8_BAR; PG8_SCHED;
;         }
	s_add_i32 s26, s55, s28
	v_lshl_add_u64 v[196:197], v[196:197], 0, s[8:9]
	s_mov_b32 m0, s26
	ds_read_b128 v[160:163], v201 offset:49152
	ds_read_b128 v[164:167], v201 offset:50176
	ds_read_b128 v[168:171], v201 offset:51200
	ds_read_b128 v[172:175], v201 offset:52224
	ds_read_b128 v[192:195], v201 offset:53248
	ds_read_b128 v[202:205], v201 offset:54272
	ds_read_b128 v[206:209], v201 offset:55296
	ds_read_b128 v[210:213], v201 offset:56320
	global_load_lds_dwordx4 v[196:197], off
	s_add_i32 m0, s26, 0x2000
	s_add_u32 s22, s22, 0x40080
	v_lshl_add_u64 v[196:197], v[214:215], 0, s[8:9]
	s_addc_u32 s23, s23, 0
	s_add_i32 s26, s56, s28
	global_load_lds_dwordx4 v[196:197], off
	v_lshl_add_u64 v[196:197], s[22:23], 0, v[178:179]
	s_mov_b32 m0, s26
	s_nop 0
	global_load_lds_dwordx4 v[196:197], off
	v_lshl_add_u64 v[196:197], s[22:23], 0, v[176:177]
	s_add_i32 m0, s26, 0x2000
	s_nop 0
	global_load_lds_dwordx4 v[196:197], off
	v_lshl_add_u64 v[196:197], v[216:217], 0, s[8:9]
	s_mov_b32 m0, s41
	s_nop 0
	global_load_lds_dwordx4 v[196:197], off
	v_lshl_add_u64 v[196:197], v[218:219], 0, s[8:9]
	s_mov_b32 m0, s42
	s_nop 0
	global_load_lds_dwordx4 v[196:197], off
	s_waitcnt vmcnt(8)
	s_waitcnt lgkmcnt(0)
	s_barrier
	v_mfma_f32_16x16x32_bf16 v[60:63], v[128:131], v[160:163], v[60:63]
	v_mfma_f32_16x16x32_bf16 v[52:55], v[136:139], v[160:163], v[52:55]
	v_mfma_f32_16x16x32_bf16 v[44:47], v[128:131], v[168:171], v[44:47]
	v_mfma_f32_16x16x32_bf16 v[36:39], v[136:139], v[168:171], v[36:39]
	v_mfma_f32_16x16x32_bf16 v[28:31], v[128:131], v[192:195], v[28:31]
	v_mfma_f32_16x16x32_bf16 v[20:23], v[136:139], v[192:195], v[20:23]
	v_mfma_f32_16x16x32_bf16 v[8:11], v[128:131], v[206:209], v[8:11]
	v_mfma_f32_16x16x32_bf16 v[0:3], v[136:139], v[206:209], v[0:3]
	v_mfma_f32_16x16x32_bf16 v[60:63], v[132:135], v[164:167], v[60:63]
	v_mfma_f32_16x16x32_bf16 v[52:55], v[140:143], v[164:167], v[52:55]
	v_mfma_f32_16x16x32_bf16 v[44:47], v[132:135], v[172:175], v[44:47]
	v_mfma_f32_16x16x32_bf16 v[36:39], v[140:143], v[172:175], v[36:39]
	v_mfma_f32_16x16x32_bf16 v[28:31], v[132:135], v[202:205], v[28:31]
	v_mfma_f32_16x16x32_bf16 v[20:23], v[140:143], v[202:205], v[20:23]
	v_mfma_f32_16x16x32_bf16 v[8:11], v[132:135], v[210:213], v[8:11]
	v_mfma_f32_16x16x32_bf16 v[0:3], v[140:143], v[210:213], v[0:3]
	v_mfma_f32_16x16x32_bf16 v[56:59], v[144:147], v[160:163], v[56:59]
	v_mfma_f32_16x16x32_bf16 v[48:51], v[152:155], v[160:163], v[48:51]
	v_mfma_f32_16x16x32_bf16 v[40:43], v[144:147], v[168:171], v[40:43]
	v_mfma_f32_16x16x32_bf16 v[32:35], v[152:155], v[168:171], v[32:35]
	v_mfma_f32_16x16x32_bf16 v[24:27], v[144:147], v[192:195], v[24:27]
	v_mfma_f32_16x16x32_bf16 v[16:19], v[152:155], v[192:195], v[16:19]
	v_mfma_f32_16x16x32_bf16 v[4:7], v[144:147], v[206:209], v[4:7]
	v_mfma_f32_16x16x32_bf16 v[12:15], v[152:155], v[206:209], v[12:15]
	v_mfma_f32_16x16x32_bf16 v[56:59], v[148:151], v[164:167], v[56:59]
	v_mfma_f32_16x16x32_bf16 v[48:51], v[156:159], v[164:167], v[48:51]
	v_mfma_f32_16x16x32_bf16 v[40:43], v[148:151], v[172:175], v[40:43]
	v_mfma_f32_16x16x32_bf16 v[32:35], v[156:159], v[172:175], v[32:35]
	v_mfma_f32_16x16x32_bf16 v[24:27], v[148:151], v[202:205], v[24:27]
	v_mfma_f32_16x16x32_bf16 v[16:19], v[156:159], v[202:205], v[16:19]
	v_mfma_f32_16x16x32_bf16 v[4:7], v[148:151], v[210:213], v[4:7]
	v_mfma_f32_16x16x32_bf16 v[12:15], v[156:159], v[210:213], v[12:15]
	s_barrier
	s_add_i32 s54, s54, 2
	s_add_u32 s24, s24, 0x100
	s_addc_u32 s25, s25, 0
	s_add_u32 s52, s52, 0x100
	s_addc_u32 s53, s53, 0
	s_cmp_gt_u32 s54, 13
	s_cbranch_scc0 .LBB0_434
	s_and_b64 vcc, exec, s[10:11]
	s_cbranch_vccz .LBB0_437
	s_barrier

; #define PG8_STAGE(bufoff, gbase, voff) do { _Pragma("unroll") for (int _i = 0; _i < 2; ++_i) \
;         __builtin_amdgcn_global_load_lds((const unsigned*)((const char*)(gbase) + (voff)[_i]), (PG8_LAS unsigned*)(lds + (bufoff) + ldsw + _i * 8192), 16, 0, 0); } while (0)
; #define PG8_LDA(dst, b, h) do { _Pragma("unroll") for (int m = 0; m < 4; ++m) _Pragma("unroll") for (int k = 0; k < 2; ++k) dst[m][k] = *(const PG8_LAS bf16x8*)(lds + PG8_SA(b, h) + aoff + m * 2048 + k * 1024); } while (0)
; #define PG8_WAIT_V(n) asm volatile("s_waitcnt vmcnt(" #n ")" ::: "memory")
; #define PG8_WAIT_L(n) asm volatile("s_waitcnt lgkmcnt(" #n ")" ::: "memory")
; #define PG8_BAR __builtin_amdgcn_s_barrier()
; #define PG8_SCHED __builtin_amdgcn_sched_barrier(0)
;     __device__ __forceinline__ void operator()(const f32x4 (&acc)[2][2][4][2], const Unit& u, int wr, int wc, int fr, int fq, const bool reuse, PG8_LAS float* rscr, PG8_LAS const float* gains) const {
;     ...
;                 f32x4 rs4[2][4];
; #pragma unroll
;                 for (int ai = 0; ai < 2; ++ai)
; #pragma unroll
;                     for (int m = 0; m < 4; ++m) { const int r = u.pm * BM + ai * HALF + wr * 64 + m * 16 + fr; rs4[ai][m] = *(const f32x4*)(rs + (size_t)(row_base + r) * 16 + 4 * fq); }
;     ...
;             PG8_WAIT_V(8); PG8_WAIT_L(0); PG8_BAR; PG8_MMA(0, 0, At, B0); PG8_MMA(0, 1, At, B1); PG8_BAR; PG8_SCHED;
;             PG8_LDA(At, 0, 1); PG8_STAGE(PG8_SB(0, 0), b2, voffB); PG8_STAGE(PG8_SB(0, 1), b2 + hstepB, voffB); PG8_STAGE(PG8_SA(0, 0), a2, voffA);
;             PG8_WAIT_V(8); PG8_WAIT_L(0); PG8_BAR; PG8_MMA(1, 0, At, B0); PG8_MMA(1, 1, At, B1); PG8_BAR; PG8_SCHED;
.Lpkb_da:
	s_waitcnt lgkmcnt(0)
	s_barrier
	v_mfma_f32_16x16x32_f16 v[132:135], v[112:115], v[160:163], v[132:135]
	v_mfma_f32_16x16x32_f16 v[128:131], v[120:123], v[160:163], v[128:131]
	v_mfma_f32_16x16x32_f16 v[100:103], v[112:115], v[168:171], v[100:103]
	v_mfma_f32_16x16x32_f16 v[96:99], v[120:123], v[168:171], v[96:99]
	v_mfma_f32_16x16x32_f16 v[84:87], v[112:115], v[202:205], v[84:87]
	v_mfma_f32_16x16x32_f16 v[80:83], v[120:123], v[202:205], v[80:83]
	v_mfma_f32_16x16x32_f16 v[68:71], v[112:115], v[210:213], v[68:71]
	v_mfma_f32_16x16x32_f16 v[64:67], v[120:123], v[210:213], v[64:67]
	v_mfma_f32_16x16x32_f16 v[132:135], v[116:119], v[164:167], v[132:135]
	v_mfma_f32_16x16x32_f16 v[128:131], v[124:127], v[164:167], v[128:131]
	v_mfma_f32_16x16x32_f16 v[100:103], v[116:119], v[192:195], v[100:103]
	v_mfma_f32_16x16x32_f16 v[96:99], v[124:127], v[192:195], v[96:99]
	v_mfma_f32_16x16x32_f16 v[84:87], v[116:119], v[206:209], v[84:87]
	v_mfma_f32_16x16x32_f16 v[80:83], v[124:127], v[206:209], v[80:83]
	v_mfma_f32_16x16x32_f16 v[68:71], v[116:119], v[214:217], v[68:71]
	v_mfma_f32_16x16x32_f16 v[64:67], v[124:127], v[214:217], v[64:67]
	v_mfma_f32_16x16x32_f16 v[140:143], v[144:147], v[160:163], v[140:143]
	v_mfma_f32_16x16x32_f16 v[136:139], v[152:155], v[160:163], v[136:139]
	v_mfma_f32_16x16x32_f16 v[108:111], v[144:147], v[168:171], v[108:111]
	v_mfma_f32_16x16x32_f16 v[104:107], v[152:155], v[168:171], v[104:107]
	v_mfma_f32_16x16x32_f16 v[92:95], v[144:147], v[202:205], v[92:95]
	v_mfma_f32_16x16x32_f16 v[88:91], v[152:155], v[202:205], v[88:91]
	v_mfma_f32_16x16x32_f16 v[76:79], v[144:147], v[210:213], v[76:79]
	v_mfma_f32_16x16x32_f16 v[72:75], v[152:155], v[210:213], v[72:75]
	v_mfma_f32_16x16x32_f16 v[140:143], v[148:151], v[164:167], v[140:143]
	v_mfma_f32_16x16x32_f16 v[136:139], v[156:159], v[164:167], v[136:139]
	v_mfma_f32_16x16x32_f16 v[108:111], v[148:151], v[192:195], v[108:111]
	v_mfma_f32_16x16x32_f16 v[104:107], v[156:159], v[192:195], v[104:107]
	v_mfma_f32_16x16x32_f16 v[92:95], v[148:151], v[206:209], v[92:95]
	v_mfma_f32_16x16x32_f16 v[88:91], v[156:159], v[206:209], v[88:91]
	v_mfma_f32_16x16x32_f16 v[76:79], v[148:151], v[214:217], v[76:79]
	v_mfma_f32_16x16x32_f16 v[72:75], v[156:159], v[214:217], v[72:75]
	s_barrier
	s_add_i32 s57, s51, s28
	v_lshl_add_u64 v[218:219], s[22:23], 0, v[174:175]
	s_mov_b32 m0, s57
	ds_read_b128 v[160:163], v200 offset:16384
	ds_read_b128 v[164:167], v200 offset:17408
	ds_read_b128 v[168:171], v200 offset:18432
	ds_read_b128 v[192:195], v200 offset:19456
	ds_read_b128 v[202:205], v200 offset:20480
	ds_read_b128 v[206:209], v200 offset:21504
	ds_read_b128 v[210:213], v200 offset:22528
	ds_read_b128 v[214:217], v200 offset:23552
	global_load_lds_dwordx4 v[218:219], off
	s_add_i32 m0, s57, 0x2000
	s_add_u32 s58, s22, 0x10000
	v_lshl_add_u64 v[220:221], s[22:23], 0, v[178:179]
	s_addc_u32 s59, s23, 0
	s_add_i32 s57, s52, s28
	global_load_lds_dwordx4 v[220:221], off
	v_lshl_add_u64 v[222:223], s[58:59], 0, v[174:175]
	s_mov_b32 m0, s57
	v_lshl_add_u64 v[224:225], s[26:27], 0, v[176:177]
	global_load_lds_dwordx4 v[222:223], off
	v_lshl_add_u64 v[222:223], s[58:59], 0, v[178:179]
	s_add_i32 m0, s57, 0x2000
	s_nop 0
	global_load_lds_dwordx4 v[222:223], off
	v_lshl_add_u64 v[222:223], s[26:27], 0, v[172:173]
	s_mov_b32 m0, s29
	s_nop 0
	global_load_lds_dwordx4 v[222:223], off
	s_mov_b32 m0, s41
	s_nop 0
	global_load_lds_dwordx4 v[224:225], off
	s_cmp_eq_u32 s56, 10
	s_cbranch_scc0 .Lrs_n
	s_cmp_lg_u32 s54, s38
	s_cbranch_scc0 .Lrs_n
	s_bitset1_b32 s101, 17
	s_lshl_b32 s32, s54, 8
	s_add_i32 s32, s32, s45
	s_bfe_u32 vcc_lo, s29, 0x2000a
	s_and_b32 vcc_hi, vcc_lo, 1
	s_lshl_b32 vcc_hi, vcc_hi, 5
	s_lshr_b32 m0, vcc_lo, 1
	s_lshl_b32 m0, m0, 7
	s_add_i32 vcc_hi, vcc_hi, m0
	s_add_i32 s32, s32, vcc_hi
	v_or_b32_e32 v228, s32, v196
	v_add_u32_e32 v230, 16, v228
	v_lshlrev_b32_e32 v228, 6, v228
	v_lshlrev_b32_e32 v230, 6, v230
	v_mov_b32_e32 v229, 0
	v_mov_b32_e32 v231, 0
	v_lshl_add_u64 v[228:229], v[228:229], 0, v[182:183]
	v_lshl_add_u64 v[230:231], v[230:231], 0, v[182:183]
	s_lshl_b32 vcc_lo, vcc_lo, 11
	s_lshr_b32 vcc_hi, s29, 12
	s_lshl_b32 vcc_hi, vcc_hi, 13
	s_add_i32 vcc_lo, vcc_lo, vcc_hi
	s_add_i32 m0, vcc_lo, 0x22000
	s_nop 0
	global_load_lds_dwordx4 v[228:229], off
	s_add_i32 m0, m0, 0x400
	s_nop 0
	global_load_lds_dwordx4 v[230:231], off

; #define PG8_STAGE(bufoff, gbase, voff) do { _Pragma("unroll") for (int _i = 0; _i < 2; ++_i) \
;         __builtin_amdgcn_global_load_lds((const unsigned*)((const char*)(gbase) + (voff)[_i]), (PG8_LAS unsigned*)(lds + (bufoff) + ldsw + _i * 8192), 16, 0, 0); } while (0)
; #define PG8_LDA(dst, b, h) do { _Pragma("unroll") for (int m = 0; m < 4; ++m) _Pragma("unroll") for (int k = 0; k < 2; ++k) dst[m][k] = *(const PG8_LAS bf16x8*)(lds + PG8_SA(b, h) + aoff + m * 2048 + k * 1024); } while (0)
; #define PG8_LDB(dst, b, h) do { _Pragma("unroll") for (int n = 0; n < 2; ++n) _Pragma("unroll") for (int k = 0; k < 2; ++k) dst[n][k] = *(const PG8_LAS bf16x8*)(lds + PG8_SB(b, h) + boff + n * 2048 + k * 1024); } while (0)
; #define PG8_WAIT_V(n) asm volatile("s_waitcnt vmcnt(" #n ")" ::: "memory")
; #define PG8_WAIT_L(n) asm volatile("s_waitcnt lgkmcnt(" #n ")" ::: "memory")
; #define PG8_BAR __builtin_amdgcn_s_barrier()
; #define PG8_SCHED __builtin_amdgcn_sched_barrier(0)
;     ...
;             PG8_WAIT_V(8); PG8_WAIT_L(0); PG8_BAR; PG8_MMA(1, 0, At, B0); PG8_MMA(1, 1, At, B1); PG8_BAR; PG8_SCHED;
;             PG8_LDB(B0, 1, 0); PG8_LDB(B1, 1, 1); PG8_SCHED; PG8_LDA(At, 1, 0); PG8_STAGE(PG8_SA(0, 1), a2 + hstep, voffA);
;             PG8_WAIT_V(8); PG8_WAIT_L(0); PG8_BAR; PG8_MMA(0, 0, At, B0); PG8_MMA(0, 1, At, B1); PG8_BAR; PG8_SCHED;
.Lpkb_db:
	s_waitcnt lgkmcnt(0)
	s_barrier
	v_mfma_f32_16x16x32_f16 v[52:55], v[112:115], v[160:163], v[52:55]
	v_mfma_f32_16x16x32_f16 v[48:51], v[120:123], v[160:163], v[48:51]
	v_mfma_f32_16x16x32_f16 v[36:39], v[112:115], v[168:171], v[36:39]
	v_mfma_f32_16x16x32_f16 v[32:35], v[120:123], v[168:171], v[32:35]
	v_mfma_f32_16x16x32_f16 v[20:23], v[112:115], v[202:205], v[20:23]
	v_mfma_f32_16x16x32_f16 v[16:19], v[120:123], v[202:205], v[16:19]
	v_mfma_f32_16x16x32_f16 v[4:7], v[112:115], v[210:213], v[4:7]
	v_mfma_f32_16x16x32_f16 v[0:3], v[120:123], v[210:213], v[0:3]
	v_mfma_f32_16x16x32_f16 v[52:55], v[116:119], v[164:167], v[52:55]
	v_mfma_f32_16x16x32_f16 v[48:51], v[124:127], v[164:167], v[48:51]
	v_mfma_f32_16x16x32_f16 v[36:39], v[116:119], v[192:195], v[36:39]
	v_mfma_f32_16x16x32_f16 v[32:35], v[124:127], v[192:195], v[32:35]
	v_mfma_f32_16x16x32_f16 v[20:23], v[116:119], v[206:209], v[20:23]
	v_mfma_f32_16x16x32_f16 v[16:19], v[124:127], v[206:209], v[16:19]
	v_mfma_f32_16x16x32_f16 v[4:7], v[116:119], v[214:217], v[4:7]
	v_mfma_f32_16x16x32_f16 v[0:3], v[124:127], v[214:217], v[0:3]
	v_mfma_f32_16x16x32_f16 v[60:63], v[144:147], v[160:163], v[60:63]
	v_mfma_f32_16x16x32_f16 v[56:59], v[152:155], v[160:163], v[56:59]
	v_mfma_f32_16x16x32_f16 v[44:47], v[144:147], v[168:171], v[44:47]
	v_mfma_f32_16x16x32_f16 v[40:43], v[152:155], v[168:171], v[40:43]
	v_mfma_f32_16x16x32_f16 v[28:31], v[144:147], v[202:205], v[28:31]
	v_mfma_f32_16x16x32_f16 v[24:27], v[152:155], v[202:205], v[24:27]
	v_mfma_f32_16x16x32_f16 v[12:15], v[144:147], v[210:213], v[12:15]
	v_mfma_f32_16x16x32_f16 v[8:11], v[152:155], v[210:213], v[8:11]
	v_mfma_f32_16x16x32_f16 v[60:63], v[148:151], v[164:167], v[60:63]
	v_mfma_f32_16x16x32_f16 v[56:59], v[156:159], v[164:167], v[56:59]
	v_mfma_f32_16x16x32_f16 v[44:47], v[148:151], v[192:195], v[44:47]
	v_mfma_f32_16x16x32_f16 v[40:43], v[156:159], v[192:195], v[40:43]
	v_mfma_f32_16x16x32_f16 v[28:31], v[148:151], v[206:209], v[28:31]
	v_mfma_f32_16x16x32_f16 v[24:27], v[156:159], v[206:209], v[24:27]
	v_mfma_f32_16x16x32_f16 v[12:15], v[148:151], v[214:217], v[12:15]
	v_mfma_f32_16x16x32_f16 v[8:11], v[156:159], v[214:217], v[8:11]
	s_barrier
	s_add_i32 s57, 0, 0x18000
	s_add_i32 s58, 0, 0x1c000
	v_add_u32_e32 v124, s57, v197
	v_add_u32_e32 v156, s58, v197
	ds_read_b128 v[112:115], v124
	ds_read_b128 v[116:119], v124 offset:1024
	ds_read_b128 v[120:123], v124 offset:2048
	ds_read_b128 v[124:127], v124 offset:3072
	ds_read_b128 v[144:147], v156
	ds_read_b128 v[148:151], v156 offset:1024
	ds_read_b128 v[152:155], v156 offset:2048
	ds_read_b128 v[156:159], v156 offset:3072
	s_add_u32 s26, s26, 0x40000
	s_addc_u32 s27, s27, 0
	s_mov_b32 m0, s42
	v_lshl_add_u64 v[226:227], s[26:27], 0, v[172:173]
	ds_read_b128 v[160:163], v200 offset:32768
	ds_read_b128 v[164:167], v200 offset:33792
	ds_read_b128 v[168:171], v200 offset:34816
	ds_read_b128 v[192:195], v200 offset:35840
	ds_read_b128 v[202:205], v200 offset:36864
	ds_read_b128 v[206:209], v200 offset:37888
	ds_read_b128 v[210:213], v200 offset:38912
	ds_read_b128 v[214:217], v200 offset:39936
	global_load_lds_dwordx4 v[226:227], off
	v_lshl_add_u64 v[226:227], s[26:27], 0, v[176:177]
	s_mov_b32 m0, s43
	s_nop 0
	global_load_lds_dwordx4 v[226:227], off
	s_bfe_u32 vcc_lo, s101, 0x20010
	s_cmp_eq_u32 vcc_lo, 0
	s_cbranch_scc1 .Lpkb_w8c
	s_cmp_eq_u32 vcc_lo, 1
	s_cbranch_scc1 .Lpkb_w9c
	s_cmp_eq_u32 vcc_lo, 2
	s_cbranch_scc1 .Lpkb_w10c
	s_waitcnt vmcnt(11)
	s_branch .Lpkb_dc

; #define PG8_STAGE(bufoff, gbase, voff) do { _Pragma("unroll") for (int _i = 0; _i < 2; ++_i) \
;         __builtin_amdgcn_global_load_lds((const unsigned*)((const char*)(gbase) + (voff)[_i]), (PG8_LAS unsigned*)(lds + (bufoff) + ldsw + _i * 8192), 16, 0, 0); } while (0)
; #define PG8_LDA(dst, b, h) do { _Pragma("unroll") for (int m = 0; m < 4; ++m) _Pragma("unroll") for (int k = 0; k < 2; ++k) dst[m][k] = *(const PG8_LAS bf16x8*)(lds + PG8_SA(b, h) + aoff + m * 2048 + k * 1024); } while (0)
; #define PG8_WAIT_V(n) asm volatile("s_waitcnt vmcnt(" #n ")" ::: "memory")
; #define PG8_WAIT_L(n) asm volatile("s_waitcnt lgkmcnt(" #n ")" ::: "memory")
; #define PG8_BAR __builtin_amdgcn_s_barrier()
; #define PG8_SCHED __builtin_amdgcn_sched_barrier(0)
;     ...
;             PG8_WAIT_V(8); PG8_WAIT_L(0); PG8_BAR; PG8_MMA(0, 0, At, B0); PG8_MMA(0, 1, At, B1); PG8_BAR; PG8_SCHED;
;             PG8_LDA(At, 1, 1); PG8_STAGE(PG8_SB(1, 0), b3, voffB); PG8_STAGE(PG8_SB(1, 1), b3 + hstepB, voffB); PG8_STAGE(PG8_SA(1, 0), a3, voffA);
;             PG8_WAIT_V(8); PG8_WAIT_L(0); PG8_BAR; PG8_MMA(1, 0, At, B0); PG8_MMA(1, 1, At, B1); PG8_BAR; PG8_SCHED;
.Lpkb_dc:
	s_waitcnt lgkmcnt(0)
	s_barrier
	v_mfma_f32_16x16x32_f16 v[132:135], v[112:115], v[160:163], v[132:135]
	v_mfma_f32_16x16x32_f16 v[128:131], v[120:123], v[160:163], v[128:131]
	v_mfma_f32_16x16x32_f16 v[100:103], v[112:115], v[168:171], v[100:103]
	v_mfma_f32_16x16x32_f16 v[96:99], v[120:123], v[168:171], v[96:99]
	v_mfma_f32_16x16x32_f16 v[84:87], v[112:115], v[202:205], v[84:87]
	v_mfma_f32_16x16x32_f16 v[80:83], v[120:123], v[202:205], v[80:83]
	v_mfma_f32_16x16x32_f16 v[68:71], v[112:115], v[210:213], v[68:71]
	v_mfma_f32_16x16x32_f16 v[64:67], v[120:123], v[210:213], v[64:67]
	v_mfma_f32_16x16x32_f16 v[132:135], v[116:119], v[164:167], v[132:135]
	v_mfma_f32_16x16x32_f16 v[128:131], v[124:127], v[164:167], v[128:131]
	v_mfma_f32_16x16x32_f16 v[100:103], v[116:119], v[192:195], v[100:103]
	v_mfma_f32_16x16x32_f16 v[96:99], v[124:127], v[192:195], v[96:99]
	v_mfma_f32_16x16x32_f16 v[84:87], v[116:119], v[206:209], v[84:87]
	v_mfma_f32_16x16x32_f16 v[80:83], v[124:127], v[206:209], v[80:83]
	v_mfma_f32_16x16x32_f16 v[68:71], v[116:119], v[214:217], v[68:71]
	v_mfma_f32_16x16x32_f16 v[64:67], v[124:127], v[214:217], v[64:67]
	v_mfma_f32_16x16x32_f16 v[140:143], v[144:147], v[160:163], v[140:143]
	v_mfma_f32_16x16x32_f16 v[136:139], v[152:155], v[160:163], v[136:139]
	v_mfma_f32_16x16x32_f16 v[108:111], v[144:147], v[168:171], v[108:111]
	v_mfma_f32_16x16x32_f16 v[104:107], v[152:155], v[168:171], v[104:107]
	v_mfma_f32_16x16x32_f16 v[92:95], v[144:147], v[202:205], v[92:95]
	v_mfma_f32_16x16x32_f16 v[88:91], v[152:155], v[202:205], v[88:91]
	v_mfma_f32_16x16x32_f16 v[76:79], v[144:147], v[210:213], v[76:79]
	v_mfma_f32_16x16x32_f16 v[72:75], v[152:155], v[210:213], v[72:75]
	v_mfma_f32_16x16x32_f16 v[140:143], v[148:151], v[164:167], v[140:143]
	v_mfma_f32_16x16x32_f16 v[136:139], v[156:159], v[164:167], v[136:139]
	v_mfma_f32_16x16x32_f16 v[108:111], v[148:151], v[192:195], v[108:111]
	v_mfma_f32_16x16x32_f16 v[104:107], v[156:159], v[192:195], v[104:107]
	v_mfma_f32_16x16x32_f16 v[92:95], v[148:151], v[206:209], v[92:95]
	v_mfma_f32_16x16x32_f16 v[88:91], v[156:159], v[206:209], v[88:91]
	v_mfma_f32_16x16x32_f16 v[76:79], v[148:151], v[214:217], v[76:79]
	v_mfma_f32_16x16x32_f16 v[72:75], v[156:159], v[214:217], v[72:75]
	s_barrier
	s_add_i32 s26, s57, s28
	v_lshl_add_u64 v[218:219], v[218:219], 0, s[10:11]
	s_mov_b32 m0, s26
	ds_read_b128 v[160:163], v200 offset:49152
	ds_read_b128 v[164:167], v200 offset:50176
	ds_read_b128 v[168:171], v200 offset:51200
	ds_read_b128 v[192:195], v200 offset:52224
	ds_read_b128 v[202:205], v200 offset:53248
	ds_read_b128 v[206:209], v200 offset:54272
	ds_read_b128 v[210:213], v200 offset:55296
	ds_read_b128 v[214:217], v200 offset:56320
	global_load_lds_dwordx4 v[218:219], off
	s_add_i32 m0, s26, 0x2000
	s_add_u32 s22, s22, 0x10080
	v_lshl_add_u64 v[218:219], v[220:221], 0, s[10:11]
	s_addc_u32 s23, s23, 0
	s_add_i32 s26, s58, s28
	global_load_lds_dwordx4 v[218:219], off
	v_lshl_add_u64 v[218:219], s[22:23], 0, v[174:175]
	s_mov_b32 m0, s26
	s_nop 0
	global_load_lds_dwordx4 v[218:219], off
	v_lshl_add_u64 v[218:219], s[22:23], 0, v[178:179]
	s_add_i32 m0, s26, 0x2000
	s_nop 0
	global_load_lds_dwordx4 v[218:219], off
	v_lshl_add_u64 v[218:219], v[222:223], 0, s[10:11]
	s_mov_b32 m0, s48
	s_nop 0
	global_load_lds_dwordx4 v[218:219], off
	v_lshl_add_u64 v[218:219], v[224:225], 0, s[10:11]
	s_mov_b32 m0, s49
	s_nop 0
	global_load_lds_dwordx4 v[218:219], off
	s_bitcmp1_b32 s101, 17
	s_cbranch_scc0 .Lpkb_w8e
	s_waitcnt vmcnt(10)
	s_branch .Lpkb_de

; #define PG8_WAIT_V(n) asm volatile("s_waitcnt vmcnt(" #n ")" ::: "memory")
; #define PG8_WAIT_L(n) asm volatile("s_waitcnt lgkmcnt(" #n ")" ::: "memory")
; #define PG8_BAR __builtin_amdgcn_s_barrier()
; #define PG8_SCHED __builtin_amdgcn_sched_barrier(0)
;     ...
;             PG8_WAIT_V(8); PG8_WAIT_L(0); PG8_BAR; PG8_MMA(1, 0, At, B0); PG8_MMA(1, 1, At, B1); PG8_BAR; PG8_SCHED;
;         }
.Lpkb_de:
	s_waitcnt lgkmcnt(0)
	s_barrier
	v_mfma_f32_16x16x32_f16 v[52:55], v[112:115], v[160:163], v[52:55]
	v_mfma_f32_16x16x32_f16 v[48:51], v[120:123], v[160:163], v[48:51]
	v_mfma_f32_16x16x32_f16 v[36:39], v[112:115], v[168:171], v[36:39]
	v_mfma_f32_16x16x32_f16 v[32:35], v[120:123], v[168:171], v[32:35]
	v_mfma_f32_16x16x32_f16 v[20:23], v[112:115], v[202:205], v[20:23]
	v_mfma_f32_16x16x32_f16 v[16:19], v[120:123], v[202:205], v[16:19]
	v_mfma_f32_16x16x32_f16 v[4:7], v[112:115], v[210:213], v[4:7]
	v_mfma_f32_16x16x32_f16 v[0:3], v[120:123], v[210:213], v[0:3]
	v_mfma_f32_16x16x32_f16 v[52:55], v[116:119], v[164:167], v[52:55]
	v_mfma_f32_16x16x32_f16 v[48:51], v[124:127], v[164:167], v[48:51]
	v_mfma_f32_16x16x32_f16 v[36:39], v[116:119], v[192:195], v[36:39]
	v_mfma_f32_16x16x32_f16 v[32:35], v[124:127], v[192:195], v[32:35]
	v_mfma_f32_16x16x32_f16 v[20:23], v[116:119], v[206:209], v[20:23]
	v_mfma_f32_16x16x32_f16 v[16:19], v[124:127], v[206:209], v[16:19]
	v_mfma_f32_16x16x32_f16 v[4:7], v[116:119], v[214:217], v[4:7]
	v_mfma_f32_16x16x32_f16 v[0:3], v[124:127], v[214:217], v[0:3]
	v_mfma_f32_16x16x32_f16 v[60:63], v[144:147], v[160:163], v[60:63]
	v_mfma_f32_16x16x32_f16 v[56:59], v[152:155], v[160:163], v[56:59]
	v_mfma_f32_16x16x32_f16 v[44:47], v[144:147], v[168:171], v[44:47]
	v_mfma_f32_16x16x32_f16 v[40:43], v[152:155], v[168:171], v[40:43]
	v_mfma_f32_16x16x32_f16 v[28:31], v[144:147], v[202:205], v[28:31]
	v_mfma_f32_16x16x32_f16 v[24:27], v[152:155], v[202:205], v[24:27]
	v_mfma_f32_16x16x32_f16 v[12:15], v[144:147], v[210:213], v[12:15]
	v_mfma_f32_16x16x32_f16 v[8:11], v[152:155], v[210:213], v[8:11]
	v_mfma_f32_16x16x32_f16 v[60:63], v[148:151], v[164:167], v[60:63]
	v_mfma_f32_16x16x32_f16 v[56:59], v[156:159], v[164:167], v[56:59]
	v_mfma_f32_16x16x32_f16 v[44:47], v[148:151], v[192:195], v[44:47]
	v_mfma_f32_16x16x32_f16 v[40:43], v[156:159], v[192:195], v[40:43]
	v_mfma_f32_16x16x32_f16 v[28:31], v[148:151], v[206:209], v[28:31]
	v_mfma_f32_16x16x32_f16 v[24:27], v[156:159], v[206:209], v[24:27]
	v_mfma_f32_16x16x32_f16 v[12:15], v[148:151], v[214:217], v[12:15]
	v_mfma_f32_16x16x32_f16 v[8:11], v[156:159], v[214:217], v[8:11]
	s_barrier
	s_bitcmp1_b32 s101, 16
	s_cbranch_scc0 .Lpkb_t
	s_sub_u32 s101, s101, 1

; #define PG8_STAGE(bufoff, gbase, voff) do { _Pragma("unroll") for (int _i = 0; _i < 2; ++_i) \
;         __builtin_amdgcn_global_load_lds((const unsigned*)((const char*)(gbase) + (voff)[_i]), (PG8_LAS unsigned*)(lds + (bufoff) + ldsw + _i * 8192), 16, 0, 0); } while (0)
; #define PG8_LDA(dst, b, h) do { _Pragma("unroll") for (int m = 0; m < 4; ++m) _Pragma("unroll") for (int k = 0; k < 2; ++k) dst[m][k] = *(const PG8_LAS bf16x8*)(lds + PG8_SA(b, h) + aoff + m * 2048 + k * 1024); } while (0)
; #define PG8_LDB(dst, b, h) do { _Pragma("unroll") for (int n = 0; n < 2; ++n) _Pragma("unroll") for (int k = 0; k < 2; ++k) dst[n][k] = *(const PG8_LAS bf16x8*)(lds + PG8_SB(b, h) + boff + n * 2048 + k * 1024); } while (0)
; #define PG8_WAIT_V(n) asm volatile("s_waitcnt vmcnt(" #n ")" ::: "memory")
; #define PG8_WAIT_L(n) asm volatile("s_waitcnt lgkmcnt(" #n ")" ::: "memory")
; #define PG8_BAR __builtin_amdgcn_s_barrier()
; #define PG8_SCHED __builtin_amdgcn_sched_barrier(0)
;     ...
;         const bool has_next = S.next(ui + 1, nxt);
;         const char* nA = has_next ? (const char*)g.A + (size_t)nxt.pm * tstep : cA; const char* nB = has_next ? (const char*)g.Bt + (size_t)nxt.pn * tstep : cB;
;         for (int t = 0; t < nt; t += 2) {
;             const bool last = (t == nt - 2);
;             const char* a1 = cA + (size_t)(t + 1) * kstep;
;             const char* a2 = last ? nA : cA + (size_t)(t + 2) * kstep; const char* b2 = last ? nB : cB + (size_t)(t + 2) * kstep;
;             const char* a3 = a2 + kstep; const char* b3 = b2 + kstep;
;             PG8_LDB(B0, 0, 0); PG8_LDB(B1, 0, 1); PG8_SCHED; PG8_LDA(At, 0, 0); PG8_STAGE(PG8_SA(1, 1), a1 + hstep, voffA);
;             PG8_WAIT_V(8); PG8_WAIT_L(0); PG8_BAR; PG8_MMA(0, 0, At, B0); PG8_MMA(0, 1, At, B1); PG8_BAR; PG8_SCHED;
;             PG8_LDA(At, 0, 1); PG8_STAGE(PG8_SB(0, 0), b2, voffB); PG8_STAGE(PG8_SB(0, 1), b2 + hstepB, voffB); PG8_STAGE(PG8_SA(0, 0), a2, voffA);
;             PG8_WAIT_V(8); PG8_WAIT_L(0); PG8_BAR; PG8_MMA(1, 0, At, B0); PG8_MMA(1, 1, At, B1); PG8_BAR; PG8_SCHED;
;             PG8_LDB(B0, 1, 0); PG8_LDB(B1, 1, 1); PG8_SCHED; PG8_LDA(At, 1, 0); PG8_STAGE(PG8_SA(0, 1), a2 + hstep, voffA);
.LBB0_732:
	v_add_u32_e32 v158, s37, v152
	v_add_u32_e32 v174, s38, v152
	ds_read_b128 v[128:131], v158
	ds_read_b128 v[148:151], v158 offset:1024
	ds_read_b128 v[154:157], v158 offset:2048
	ds_read_b128 v[158:161], v158 offset:3072
	ds_read_b128 v[162:165], v174
	ds_read_b128 v[166:169], v174 offset:1024
	ds_read_b128 v[170:173], v174 offset:2048
	ds_read_b128 v[174:177], v174 offset:3072
	s_add_u32 s20, s22, 0xfffc0080
	s_addc_u32 s21, s23, -1
	s_cmp_eq_u32 s53, 12
	s_cselect_b32 s25, s13, s21
	s_cselect_b32 s24, s49, s20
	s_cselect_b32 s21, s11, s52
	s_cselect_b32 s20, s50, s51
	v_lshl_add_u64 v[210:211], s[22:23], 0, v[140:141]
	s_add_i32 m0, s19, 0xc000
	ds_read_b128 v[178:181], v153
	ds_read_b128 v[182:185], v153 offset:1024
	ds_read_b128 v[186:189], v153 offset:2048
	ds_read_b128 v[190:193], v153 offset:3072
	ds_read_b128 v[194:197], v153 offset:4096
	ds_read_b128 v[198:201], v153 offset:5120
	ds_read_b128 v[202:205], v153 offset:6144
	ds_read_b128 v[206:209], v153 offset:7168
	global_load_lds_dwordx4 v[210:211], off
	v_lshl_add_u64 v[210:211], s[22:23], 0, v[142:143]
	s_add_i32 m0, s19, 0xe000
	s_nop 0
	global_load_lds_dwordx4 v[210:211], off
	s_waitcnt vmcnt(8)
	s_waitcnt lgkmcnt(0)
	s_barrier
	v_mfma_f32_16x16x32_bf16 v[112:115], v[128:131], v[178:181], v[112:115]
	v_mfma_f32_16x16x32_bf16 v[116:119], v[154:157], v[178:181], v[116:119]
	v_mfma_f32_16x16x32_bf16 v[108:111], v[128:131], v[186:189], v[108:111]
	v_mfma_f32_16x16x32_bf16 v[104:107], v[154:157], v[186:189], v[104:107]
	v_mfma_f32_16x16x32_bf16 v[92:95], v[128:131], v[194:197], v[92:95]
	v_mfma_f32_16x16x32_bf16 v[88:91], v[154:157], v[194:197], v[88:91]
	v_mfma_f32_16x16x32_bf16 v[76:79], v[128:131], v[202:205], v[76:79]
	v_mfma_f32_16x16x32_bf16 v[72:75], v[154:157], v[202:205], v[72:75]
	v_mfma_f32_16x16x32_bf16 v[112:115], v[148:151], v[182:185], v[112:115]
	v_mfma_f32_16x16x32_bf16 v[116:119], v[158:161], v[182:185], v[116:119]
	v_mfma_f32_16x16x32_bf16 v[108:111], v[148:151], v[190:193], v[108:111]
	v_mfma_f32_16x16x32_bf16 v[104:107], v[158:161], v[190:193], v[104:107]
	v_mfma_f32_16x16x32_bf16 v[92:95], v[148:151], v[198:201], v[92:95]
	v_mfma_f32_16x16x32_bf16 v[88:91], v[158:161], v[198:201], v[88:91]
	v_mfma_f32_16x16x32_bf16 v[76:79], v[148:151], v[206:209], v[76:79]
	v_mfma_f32_16x16x32_bf16 v[72:75], v[158:161], v[206:209], v[72:75]
	v_mfma_f32_16x16x32_bf16 v[120:123], v[162:165], v[178:181], v[120:123]
	v_mfma_f32_16x16x32_bf16 v[124:127], v[170:173], v[178:181], v[124:127]
	v_mfma_f32_16x16x32_bf16 v[100:103], v[162:165], v[186:189], v[100:103]
	v_mfma_f32_16x16x32_bf16 v[96:99], v[170:173], v[186:189], v[96:99]
	v_mfma_f32_16x16x32_bf16 v[84:87], v[162:165], v[194:197], v[84:87]
	v_mfma_f32_16x16x32_bf16 v[80:83], v[170:173], v[194:197], v[80:83]
	v_mfma_f32_16x16x32_bf16 v[68:71], v[162:165], v[202:205], v[68:71]
	v_mfma_f32_16x16x32_bf16 v[64:67], v[170:173], v[202:205], v[64:67]
	v_mfma_f32_16x16x32_bf16 v[120:123], v[166:169], v[182:185], v[120:123]
	v_mfma_f32_16x16x32_bf16 v[124:127], v[174:177], v[182:185], v[124:127]
	v_mfma_f32_16x16x32_bf16 v[100:103], v[166:169], v[190:193], v[100:103]
	v_mfma_f32_16x16x32_bf16 v[96:99], v[174:177], v[190:193], v[96:99]
	v_mfma_f32_16x16x32_bf16 v[84:87], v[166:169], v[198:201], v[84:87]
	v_mfma_f32_16x16x32_bf16 v[80:83], v[174:177], v[198:201], v[80:83]
	v_mfma_f32_16x16x32_bf16 v[68:71], v[166:169], v[206:209], v[68:71]
	v_mfma_f32_16x16x32_bf16 v[64:67], v[174:177], v[206:209], v[64:67]
	s_barrier
	s_add_i32 s54, s37, s26
	v_lshl_add_u64 v[210:211], s[20:21], 0, v[134:135]
	s_mov_b32 m0, s54
	ds_read_b128 v[178:181], v153 offset:16384
	ds_read_b128 v[182:185], v153 offset:17408
	ds_read_b128 v[186:189], v153 offset:18432
	ds_read_b128 v[190:193], v153 offset:19456
	ds_read_b128 v[194:197], v153 offset:20480
	ds_read_b128 v[198:201], v153 offset:21504
	ds_read_b128 v[202:205], v153 offset:22528
	ds_read_b128 v[206:209], v153 offset:23552
	global_load_lds_dwordx4 v[210:211], off
	s_add_i32 m0, s54, 0x2000
	s_add_u32 s54, s20, 0x40000
	v_lshl_add_u64 v[212:213], s[20:21], 0, v[132:133]
	s_addc_u32 s55, s21, 0
	s_add_i32 s56, s38, s26
	global_load_lds_dwordx4 v[212:213], off
	v_lshl_add_u64 v[214:215], s[54:55], 0, v[134:135]
	s_mov_b32 m0, s56
	v_lshl_add_u64 v[216:217], s[24:25], 0, v[132:133]
	global_load_lds_dwordx4 v[214:215], off
	v_lshl_add_u64 v[214:215], s[54:55], 0, v[132:133]
	s_add_i32 m0, s56, 0x2000
	s_nop 0
	global_load_lds_dwordx4 v[214:215], off
	v_lshl_add_u64 v[214:215], s[24:25], 0, v[134:135]
	s_mov_b32 m0, s19
	s_nop 0
	global_load_lds_dwordx4 v[214:215], off
	s_mov_b32 m0, s27
	s_nop 0
	global_load_lds_dwordx4 v[216:217], off
	s_waitcnt vmcnt(8)
	s_waitcnt lgkmcnt(0)
	s_barrier
; #define PG8_STAGE(bufoff, gbase, voff) do { _Pragma("unroll") for (int _i = 0; _i < 2; ++_i) \
;         __builtin_amdgcn_global_load_lds((const unsigned*)((const char*)(gbase) + (voff)[_i]), (PG8_LAS unsigned*)(lds + (bufoff) + ldsw + _i * 8192), 16, 0, 0); } while (0)
; #define PG8_LDA(dst, b, h) do { _Pragma("unroll") for (int m = 0; m < 4; ++m) _Pragma("unroll") for (int k = 0; k < 2; ++k) dst[m][k] = *(const PG8_LAS bf16x8*)(lds + PG8_SA(b, h) + aoff + m * 2048 + k * 1024); } while (0)
; #define PG8_WAIT_V(n) asm volatile("s_waitcnt vmcnt(" #n ")" ::: "memory")
; #define PG8_WAIT_L(n) asm volatile("s_waitcnt lgkmcnt(" #n ")" ::: "memory")
; #define PG8_BAR __builtin_amdgcn_s_barrier()
; #define PG8_SCHED __builtin_amdgcn_sched_barrier(0)
;     ...
;             PG8_WAIT_V(8); PG8_WAIT_L(0); PG8_BAR; PG8_MMA(0, 0, At, B0); PG8_MMA(0, 1, At, B1); PG8_BAR; PG8_SCHED;
;             PG8_LDA(At, 1, 1); PG8_STAGE(PG8_SB(1, 0), b3, voffB); PG8_STAGE(PG8_SB(1, 1), b3 + hstepB, voffB); PG8_STAGE(PG8_SA(1, 0), a3, voffA);
;             PG8_WAIT_V(8); PG8_WAIT_L(0); PG8_BAR; PG8_MMA(1, 0, At, B0); PG8_MMA(1, 1, At, B1); PG8_BAR; PG8_SCHED;
	v_mfma_f32_16x16x32_bf16 v[60:63], v[128:131], v[178:181], v[60:63]
	v_mfma_f32_16x16x32_bf16 v[56:59], v[154:157], v[178:181], v[56:59]
	v_mfma_f32_16x16x32_bf16 v[44:47], v[128:131], v[186:189], v[44:47]
	v_mfma_f32_16x16x32_bf16 v[40:43], v[154:157], v[186:189], v[40:43]
	v_mfma_f32_16x16x32_bf16 v[28:31], v[128:131], v[194:197], v[28:31]
	v_mfma_f32_16x16x32_bf16 v[24:27], v[154:157], v[194:197], v[24:27]
	v_mfma_f32_16x16x32_bf16 v[12:15], v[128:131], v[202:205], v[12:15]
	v_mfma_f32_16x16x32_bf16 v[8:11], v[154:157], v[202:205], v[8:11]
	v_mfma_f32_16x16x32_bf16 v[60:63], v[148:151], v[182:185], v[60:63]
	v_mfma_f32_16x16x32_bf16 v[56:59], v[158:161], v[182:185], v[56:59]
	v_mfma_f32_16x16x32_bf16 v[44:47], v[148:151], v[190:193], v[44:47]
	v_mfma_f32_16x16x32_bf16 v[40:43], v[158:161], v[190:193], v[40:43]
	v_mfma_f32_16x16x32_bf16 v[28:31], v[148:151], v[198:201], v[28:31]
	v_mfma_f32_16x16x32_bf16 v[24:27], v[158:161], v[198:201], v[24:27]
	v_mfma_f32_16x16x32_bf16 v[12:15], v[148:151], v[206:209], v[12:15]
	v_mfma_f32_16x16x32_bf16 v[8:11], v[158:161], v[206:209], v[8:11]
	v_mfma_f32_16x16x32_bf16 v[52:55], v[162:165], v[178:181], v[52:55]
	v_mfma_f32_16x16x32_bf16 v[48:51], v[170:173], v[178:181], v[48:51]
	v_mfma_f32_16x16x32_bf16 v[36:39], v[162:165], v[186:189], v[36:39]
	v_mfma_f32_16x16x32_bf16 v[32:35], v[170:173], v[186:189], v[32:35]
	v_mfma_f32_16x16x32_bf16 v[20:23], v[162:165], v[194:197], v[20:23]
	v_mfma_f32_16x16x32_bf16 v[16:19], v[170:173], v[194:197], v[16:19]
	v_mfma_f32_16x16x32_bf16 v[0:3], v[162:165], v[202:205], v[0:3]
	v_mfma_f32_16x16x32_bf16 v[4:7], v[170:173], v[202:205], v[4:7]
	v_mfma_f32_16x16x32_bf16 v[52:55], v[166:169], v[182:185], v[52:55]
	v_mfma_f32_16x16x32_bf16 v[48:51], v[174:177], v[182:185], v[48:51]
	v_mfma_f32_16x16x32_bf16 v[36:39], v[166:169], v[190:193], v[36:39]
	v_mfma_f32_16x16x32_bf16 v[32:35], v[174:177], v[190:193], v[32:35]
	v_mfma_f32_16x16x32_bf16 v[20:23], v[166:169], v[198:201], v[20:23]
	v_mfma_f32_16x16x32_bf16 v[16:19], v[174:177], v[198:201], v[16:19]
	v_mfma_f32_16x16x32_bf16 v[0:3], v[166:169], v[206:209], v[0:3]
	v_mfma_f32_16x16x32_bf16 v[4:7], v[174:177], v[206:209], v[4:7]
	s_barrier
	s_add_i32 s54, 0, 0x18000
	s_add_i32 s55, 0, 0x1c000
	v_add_u32_e32 v158, s54, v152
	v_add_u32_e32 v174, s55, v152
	ds_read_b128 v[128:131], v158
	ds_read_b128 v[148:151], v158 offset:1024
	ds_read_b128 v[154:157], v158 offset:2048
	ds_read_b128 v[158:161], v158 offset:3072
	ds_read_b128 v[162:165], v174
	ds_read_b128 v[166:169], v174 offset:1024
	ds_read_b128 v[170:173], v174 offset:2048
	ds_read_b128 v[174:177], v174 offset:3072
	s_add_u32 s24, s24, 0x40000
	s_addc_u32 s25, s25, 0
	s_mov_b32 m0, s28
	v_lshl_add_u64 v[218:219], s[24:25], 0, v[134:135]
	ds_read_b128 v[178:181], v153 offset:32768
	ds_read_b128 v[182:185], v153 offset:33792
	ds_read_b128 v[186:189], v153 offset:34816
	ds_read_b128 v[190:193], v153 offset:35840
	ds_read_b128 v[194:197], v153 offset:36864
	ds_read_b128 v[198:201], v153 offset:37888
	ds_read_b128 v[202:205], v153 offset:38912
	ds_read_b128 v[206:209], v153 offset:39936
	global_load_lds_dwordx4 v[218:219], off
	v_lshl_add_u64 v[218:219], s[24:25], 0, v[132:133]
	s_mov_b32 m0, s29
	s_nop 0
	global_load_lds_dwordx4 v[218:219], off
	s_waitcnt vmcnt(8)
	s_waitcnt lgkmcnt(0)
	s_barrier
	v_mfma_f32_16x16x32_bf16 v[112:115], v[128:131], v[178:181], v[112:115]
	v_mfma_f32_16x16x32_bf16 v[116:119], v[154:157], v[178:181], v[116:119]
	v_mfma_f32_16x16x32_bf16 v[108:111], v[128:131], v[186:189], v[108:111]
	v_mfma_f32_16x16x32_bf16 v[104:107], v[154:157], v[186:189], v[104:107]
	v_mfma_f32_16x16x32_bf16 v[92:95], v[128:131], v[194:197], v[92:95]
	v_mfma_f32_16x16x32_bf16 v[88:91], v[154:157], v[194:197], v[88:91]
	v_mfma_f32_16x16x32_bf16 v[76:79], v[128:131], v[202:205], v[76:79]
	v_mfma_f32_16x16x32_bf16 v[72:75], v[154:157], v[202:205], v[72:75]
	v_mfma_f32_16x16x32_bf16 v[112:115], v[148:151], v[182:185], v[112:115]
	v_mfma_f32_16x16x32_bf16 v[116:119], v[158:161], v[182:185], v[116:119]
	v_mfma_f32_16x16x32_bf16 v[108:111], v[148:151], v[190:193], v[108:111]
	v_mfma_f32_16x16x32_bf16 v[104:107], v[158:161], v[190:193], v[104:107]
	v_mfma_f32_16x16x32_bf16 v[92:95], v[148:151], v[198:201], v[92:95]
	v_mfma_f32_16x16x32_bf16 v[88:91], v[158:161], v[198:201], v[88:91]
	v_mfma_f32_16x16x32_bf16 v[76:79], v[148:151], v[206:209], v[76:79]
	v_mfma_f32_16x16x32_bf16 v[72:75], v[158:161], v[206:209], v[72:75]
	v_mfma_f32_16x16x32_bf16 v[120:123], v[162:165], v[178:181], v[120:123]
	v_mfma_f32_16x16x32_bf16 v[124:127], v[170:173], v[178:181], v[124:127]
	v_mfma_f32_16x16x32_bf16 v[100:103], v[162:165], v[186:189], v[100:103]
	v_mfma_f32_16x16x32_bf16 v[96:99], v[170:173], v[186:189], v[96:99]
	v_mfma_f32_16x16x32_bf16 v[84:87], v[162:165], v[194:197], v[84:87]
	v_mfma_f32_16x16x32_bf16 v[80:83], v[170:173], v[194:197], v[80:83]
	v_mfma_f32_16x16x32_bf16 v[68:71], v[162:165], v[202:205], v[68:71]
	v_mfma_f32_16x16x32_bf16 v[64:67], v[170:173], v[202:205], v[64:67]
	v_mfma_f32_16x16x32_bf16 v[120:123], v[166:169], v[182:185], v[120:123]
	v_mfma_f32_16x16x32_bf16 v[124:127], v[174:177], v[182:185], v[124:127]
	v_mfma_f32_16x16x32_bf16 v[100:103], v[166:169], v[190:193], v[100:103]
	v_mfma_f32_16x16x32_bf16 v[96:99], v[174:177], v[190:193], v[96:99]
	v_mfma_f32_16x16x32_bf16 v[84:87], v[166:169], v[198:201], v[84:87]
	v_mfma_f32_16x16x32_bf16 v[80:83], v[174:177], v[198:201], v[80:83]
	v_mfma_f32_16x16x32_bf16 v[68:71], v[166:169], v[206:209], v[68:71]
	v_mfma_f32_16x16x32_bf16 v[64:67], v[174:177], v[206:209], v[64:67]
	s_barrier
; #define PG8_STAGE(bufoff, gbase, voff) do { _Pragma("unroll") for (int _i = 0; _i < 2; ++_i) \
;         __builtin_amdgcn_global_load_lds((const unsigned*)((const char*)(gbase) + (voff)[_i]), (PG8_LAS unsigned*)(lds + (bufoff) + ldsw + _i * 8192), 16, 0, 0); } while (0)
; #define PG8_LDA(dst, b, h) do { _Pragma("unroll") for (int m = 0; m < 4; ++m) _Pragma("unroll") for (int k = 0; k < 2; ++k) dst[m][k] = *(const PG8_LAS bf16x8*)(lds + PG8_SA(b, h) + aoff + m * 2048 + k * 1024); } while (0)
; #define PG8_WAIT_V(n) asm volatile("s_waitcnt vmcnt(" #n ")" ::: "memory")
; #define PG8_WAIT_L(n) asm volatile("s_waitcnt lgkmcnt(" #n ")" ::: "memory")
; #define PG8_BAR __builtin_amdgcn_s_barrier()
; #define PG8_SCHED __builtin_amdgcn_sched_barrier(0)
;     ...
;             PG8_LDA(At, 1, 1); PG8_STAGE(PG8_SB(1, 0), b3, voffB); PG8_STAGE(PG8_SB(1, 1), b3 + hstepB, voffB); PG8_STAGE(PG8_SA(1, 0), a3, voffA);
;             PG8_WAIT_V(8); PG8_WAIT_L(0); PG8_BAR; PG8_MMA(1, 0, At, B0); PG8_MMA(1, 1, At, B1); PG8_BAR; PG8_SCHED;
;         }
	s_add_i32 s24, s54, s26
	v_lshl_add_u64 v[210:211], v[210:211], 0, s[6:7]
	s_mov_b32 m0, s24
	ds_read_b128 v[178:181], v153 offset:49152
	ds_read_b128 v[182:185], v153 offset:50176
	ds_read_b128 v[186:189], v153 offset:51200
	ds_read_b128 v[190:193], v153 offset:52224
	ds_read_b128 v[194:197], v153 offset:53248
	ds_read_b128 v[198:201], v153 offset:54272
	ds_read_b128 v[202:205], v153 offset:55296
	ds_read_b128 v[206:209], v153 offset:56320
	global_load_lds_dwordx4 v[210:211], off
	s_add_i32 m0, s24, 0x2000
	s_add_u32 s20, s20, 0x40080
	v_lshl_add_u64 v[210:211], v[212:213], 0, s[6:7]
	s_addc_u32 s21, s21, 0
	s_add_i32 s24, s55, s26
	global_load_lds_dwordx4 v[210:211], off
	v_lshl_add_u64 v[210:211], s[20:21], 0, v[134:135]
	s_mov_b32 m0, s24
	s_nop 0
	global_load_lds_dwordx4 v[210:211], off
	v_lshl_add_u64 v[210:211], s[20:21], 0, v[132:133]
	s_add_i32 m0, s24, 0x2000
	s_nop 0
	global_load_lds_dwordx4 v[210:211], off
	v_lshl_add_u64 v[210:211], v[214:215], 0, s[6:7]
	s_mov_b32 m0, s33
	s_nop 0
	global_load_lds_dwordx4 v[210:211], off
	v_lshl_add_u64 v[210:211], v[216:217], 0, s[6:7]
	s_mov_b32 m0, s34
	s_nop 0
	global_load_lds_dwordx4 v[210:211], off
	s_waitcnt vmcnt(8)
	s_waitcnt lgkmcnt(0)
	s_barrier
	v_mfma_f32_16x16x32_bf16 v[60:63], v[128:131], v[178:181], v[60:63]
	v_mfma_f32_16x16x32_bf16 v[56:59], v[154:157], v[178:181], v[56:59]
	v_mfma_f32_16x16x32_bf16 v[44:47], v[128:131], v[186:189], v[44:47]
	v_mfma_f32_16x16x32_bf16 v[40:43], v[154:157], v[186:189], v[40:43]
	v_mfma_f32_16x16x32_bf16 v[28:31], v[128:131], v[194:197], v[28:31]
	v_mfma_f32_16x16x32_bf16 v[24:27], v[154:157], v[194:197], v[24:27]
	v_mfma_f32_16x16x32_bf16 v[12:15], v[128:131], v[202:205], v[12:15]
	v_mfma_f32_16x16x32_bf16 v[8:11], v[154:157], v[202:205], v[8:11]
	v_mfma_f32_16x16x32_bf16 v[60:63], v[148:151], v[182:185], v[60:63]
	v_mfma_f32_16x16x32_bf16 v[56:59], v[158:161], v[182:185], v[56:59]
	v_mfma_f32_16x16x32_bf16 v[44:47], v[148:151], v[190:193], v[44:47]
	v_mfma_f32_16x16x32_bf16 v[40:43], v[158:161], v[190:193], v[40:43]
	v_mfma_f32_16x16x32_bf16 v[28:31], v[148:151], v[198:201], v[28:31]
	v_mfma_f32_16x16x32_bf16 v[24:27], v[158:161], v[198:201], v[24:27]
	v_mfma_f32_16x16x32_bf16 v[12:15], v[148:151], v[206:209], v[12:15]
	v_mfma_f32_16x16x32_bf16 v[8:11], v[158:161], v[206:209], v[8:11]
	v_mfma_f32_16x16x32_bf16 v[52:55], v[162:165], v[178:181], v[52:55]
	v_mfma_f32_16x16x32_bf16 v[48:51], v[170:173], v[178:181], v[48:51]
	v_mfma_f32_16x16x32_bf16 v[36:39], v[162:165], v[186:189], v[36:39]
	v_mfma_f32_16x16x32_bf16 v[32:35], v[170:173], v[186:189], v[32:35]
	v_mfma_f32_16x16x32_bf16 v[20:23], v[162:165], v[194:197], v[20:23]
	v_mfma_f32_16x16x32_bf16 v[16:19], v[170:173], v[194:197], v[16:19]
	v_mfma_f32_16x16x32_bf16 v[0:3], v[162:165], v[202:205], v[0:3]
	v_mfma_f32_16x16x32_bf16 v[4:7], v[170:173], v[202:205], v[4:7]
	v_mfma_f32_16x16x32_bf16 v[52:55], v[166:169], v[182:185], v[52:55]
	v_mfma_f32_16x16x32_bf16 v[48:51], v[174:177], v[182:185], v[48:51]
	v_mfma_f32_16x16x32_bf16 v[36:39], v[166:169], v[190:193], v[36:39]
	v_mfma_f32_16x16x32_bf16 v[32:35], v[174:177], v[190:193], v[32:35]
	v_mfma_f32_16x16x32_bf16 v[20:23], v[166:169], v[198:201], v[20:23]
	v_mfma_f32_16x16x32_bf16 v[16:19], v[174:177], v[198:201], v[16:19]
	v_mfma_f32_16x16x32_bf16 v[0:3], v[166:169], v[206:209], v[0:3]
	v_mfma_f32_16x16x32_bf16 v[4:7], v[174:177], v[206:209], v[4:7]
	s_barrier
	s_add_i32 s53, s53, 2
	s_add_u32 s22, s22, 0x100
	s_addc_u32 s23, s23, 0
	s_add_u32 s51, s51, 0x100
	s_addc_u32 s52, s52, 0
	s_cmp_gt_u32 s53, 13
	s_cbranch_scc0 .LBB0_732
	s_and_b64 vcc, exec, s[8:9]
	s_cbranch_vccz .LBB0_735
	s_barrier
